# weight-conversion loops in the layer loop pipelined: 16 loads in flight then counted waits (were 2 at a time)
# speedup vs baseline: 1.0166x; 1.0120x over previous
; #define LAS __attribute__((address_space(3)))
; __device__ __forceinline__ void transpose_item(const float* W, int K, int N, bf16_t* WT, LAS float* scr, int item, int lane, int perm_cols) {
;     const int nblk = N / 32, kb = item / nblk, nb = item % nblk, k0 = 64 * kb, n0 = 32 * nb;
; #pragma unroll 8
;     for (int i = 0; i < 32; ++i) { const int kk = 2 * i + (lane >> 5); scr[kk * 33 + (lane & 31)] = W[(size_t)(k0 + kk) * N + n0 + (lane & 31)]; }
.LBB0_338:
	s_lshl_b32 s22, s19, 1
	s_lshl_b32 s21, s18, 1
	v_or_b32_e32 v176, s22, v14
	v_or_b32_e32 v22, s21, v5
	v_mov_b32_e32 v23, v177
	s_waitcnt vmcnt(7)
	v_lshlrev_b64 v[24:25], 13, v[176:177]
	v_lshlrev_b64 v[22:23], 13, v[22:23]
	v_lshl_add_u64 v[24:25], v[12:13], 0, v[24:25]
	v_lshl_add_u64 v[22:23], v[12:13], 0, v[22:23]
	global_load_dword v80, v[24:25], off
	global_load_dword v81, v[22:23], off
	v_or_b32_e32 v26, s21, v1
	v_or_b32_e32 v27, s22, v0
	v_mad_u64_u32 v[96:97], s[24:25], v27, s60, v[4:5]
	v_mad_u64_u32 v[98:99], s[24:25], v26, s60, v[4:5]
	s_add_i32 s24, s22, 4
	s_add_i32 s23, s21, 4
	v_or_b32_e32 v176, s24, v14
	v_mov_b32_e32 v23, v177
	v_or_b32_e32 v26, s23, v1
	v_or_b32_e32 v27, s24, v0
	s_add_i32 s19, s19, 16
	s_add_i32 s18, s18, 16
	s_add_i32 s20, s20, -16
	v_or_b32_e32 v22, s23, v5
	v_lshlrev_b64 v[24:25], 13, v[176:177]
	v_lshlrev_b64 v[22:23], 13, v[22:23]
	v_lshl_add_u64 v[24:25], v[12:13], 0, v[24:25]
	v_lshl_add_u64 v[22:23], v[12:13], 0, v[22:23]
	global_load_dword v82, v[24:25], off
	global_load_dword v83, v[22:23], off
	v_mad_u64_u32 v[100:101], s[24:25], v27, s60, v[4:5]
	v_mad_u64_u32 v[102:103], s[24:25], v26, s60, v[4:5]
	s_add_i32 s24, s22, 8
	s_add_i32 s23, s21, 8
	v_or_b32_e32 v176, s24, v14
	v_mov_b32_e32 v23, v177
	v_or_b32_e32 v26, s23, v1
	v_or_b32_e32 v27, s24, v0
	v_or_b32_e32 v22, s23, v5
	v_lshlrev_b64 v[24:25], 13, v[176:177]
	v_lshlrev_b64 v[22:23], 13, v[22:23]
	v_lshl_add_u64 v[24:25], v[12:13], 0, v[24:25]
	v_lshl_add_u64 v[22:23], v[12:13], 0, v[22:23]
	global_load_dword v84, v[24:25], off
	global_load_dword v85, v[22:23], off
	v_mad_u64_u32 v[104:105], s[24:25], v27, s60, v[4:5]
	v_mad_u64_u32 v[106:107], s[24:25], v26, s60, v[4:5]
	s_add_i32 s24, s22, 12
	s_add_i32 s23, s21, 12
	v_or_b32_e32 v176, s24, v14
	v_mov_b32_e32 v23, v177
	v_or_b32_e32 v26, s23, v1
	v_or_b32_e32 v27, s24, v0
	v_or_b32_e32 v22, s23, v5
	v_lshlrev_b64 v[24:25], 13, v[176:177]
	v_lshlrev_b64 v[22:23], 13, v[22:23]
	v_lshl_add_u64 v[24:25], v[12:13], 0, v[24:25]
	v_lshl_add_u64 v[22:23], v[12:13], 0, v[22:23]
	global_load_dword v86, v[24:25], off
	global_load_dword v87, v[22:23], off
	v_mad_u64_u32 v[108:109], s[24:25], v27, s60, v[4:5]
	v_mad_u64_u32 v[110:111], s[24:25], v26, s60, v[4:5]
	s_add_i32 s24, s22, 16
	s_add_i32 s23, s21, 16
	v_or_b32_e32 v176, s24, v14
	v_mov_b32_e32 v23, v177
	v_or_b32_e32 v26, s23, v1
	v_or_b32_e32 v27, s24, v0
	v_or_b32_e32 v22, s23, v5
	v_lshlrev_b64 v[24:25], 13, v[176:177]
	v_lshlrev_b64 v[22:23], 13, v[22:23]
	v_lshl_add_u64 v[24:25], v[12:13], 0, v[24:25]
	v_lshl_add_u64 v[22:23], v[12:13], 0, v[22:23]
	global_load_dword v88, v[24:25], off
	global_load_dword v89, v[22:23], off
	v_mad_u64_u32 v[112:113], s[24:25], v27, s60, v[4:5]
	v_mad_u64_u32 v[114:115], s[24:25], v26, s60, v[4:5]
	s_add_i32 s24, s22, 20
	s_add_i32 s23, s21, 20
	v_or_b32_e32 v176, s24, v14
	v_mov_b32_e32 v23, v177
	v_or_b32_e32 v26, s23, v1
	v_or_b32_e32 v27, s24, v0
	v_or_b32_e32 v22, s23, v5
	v_lshlrev_b64 v[24:25], 13, v[176:177]
	v_lshlrev_b64 v[22:23], 13, v[22:23]
	v_lshl_add_u64 v[24:25], v[12:13], 0, v[24:25]
	v_lshl_add_u64 v[22:23], v[12:13], 0, v[22:23]
	global_load_dword v90, v[24:25], off
	global_load_dword v91, v[22:23], off
	v_mad_u64_u32 v[116:117], s[24:25], v27, s60, v[4:5]
	v_mad_u64_u32 v[118:119], s[24:25], v26, s60, v[4:5]
	s_add_i32 s24, s22, 24
	s_add_i32 s23, s21, 24
	v_or_b32_e32 v176, s24, v14
	v_mov_b32_e32 v23, v177
	v_or_b32_e32 v26, s23, v1
	v_or_b32_e32 v27, s24, v0
	s_add_i32 s22, s22, 28
	s_add_i32 s21, s21, 28
	s_cmp_lg_u32 s20, 0
	v_or_b32_e32 v22, s23, v5
	v_lshlrev_b64 v[24:25], 13, v[176:177]
	v_lshlrev_b64 v[22:23], 13, v[22:23]
	v_lshl_add_u64 v[24:25], v[12:13], 0, v[24:25]
	v_lshl_add_u64 v[22:23], v[12:13], 0, v[22:23]
	global_load_dword v92, v[24:25], off
	global_load_dword v93, v[22:23], off
	v_mad_u64_u32 v[120:121], s[24:25], v27, s60, v[4:5]
	v_mad_u64_u32 v[122:123], s[24:25], v26, s60, v[4:5]
	v_or_b32_e32 v176, s22, v14
	v_mov_b32_e32 v23, v177
	v_or_b32_e32 v27, s22, v0
	v_or_b32_e32 v26, s21, v1
	v_or_b32_e32 v22, s21, v5
	v_lshlrev_b64 v[24:25], 13, v[176:177]
	v_lshlrev_b64 v[22:23], 13, v[22:23]
	v_lshl_add_u64 v[24:25], v[12:13], 0, v[24:25]
	v_lshl_add_u64 v[22:23], v[12:13], 0, v[22:23]
	global_load_dword v94, v[24:25], off
	global_load_dword v95, v[22:23], off
	v_mad_u64_u32 v[124:125], s[22:23], v27, s60, v[4:5]
	v_mad_u64_u32 v[126:127], s[22:23], v26, s60, v[4:5]
	s_waitcnt vmcnt(15)
	ds_write_b32 v96, v80
	s_waitcnt vmcnt(14)
	ds_write_b32 v98, v81
	s_waitcnt vmcnt(13)
	ds_write_b32 v100, v82
	s_waitcnt vmcnt(12)
	ds_write_b32 v102, v83
	s_waitcnt vmcnt(11)
	ds_write_b32 v104, v84
	s_waitcnt vmcnt(10)
	ds_write_b32 v106, v85
	s_waitcnt vmcnt(9)
	ds_write_b32 v108, v86
	s_waitcnt vmcnt(8)
	ds_write_b32 v110, v87
	s_waitcnt vmcnt(7)
	ds_write_b32 v112, v88
	s_waitcnt vmcnt(6)
	ds_write_b32 v114, v89
	s_waitcnt vmcnt(5)
	ds_write_b32 v116, v90
	s_waitcnt vmcnt(4)
	ds_write_b32 v118, v91
	s_waitcnt vmcnt(3)
	ds_write_b32 v120, v92
	s_waitcnt vmcnt(2)
	ds_write_b32 v122, v93
	s_waitcnt vmcnt(1)
	ds_write_b32 v124, v94
	s_waitcnt vmcnt(0)
	ds_write_b32 v126, v95
	s_cbranch_scc1 .LBB0_338
; #define LAS __attribute__((address_space(3)))
; __device__ __forceinline__ unsigned pk2(float lo, float hi) { unsigned r; asm("v_cvt_pk_bf16_f32 %0, %1, %2" : "=v"(r) : "v"(lo), "v"(hi)); return r; }
; __device__ __forceinline__ void transpose_item(const float* W, int K, int N, bf16_t* WT, LAS float* scr, int item, int lane, int perm_cols) {
;     ...
;     asm volatile("s_waitcnt lgkmcnt(0)" ::: "memory");
;     const int c = lane & 7;
; #pragma unroll
;     for (int j = 0; j < 4; ++j) { const int n = (lane >> 3) + 8 * j; const LAS float* s = scr + (8 * c) * 33 + n;
;         u32x4 o; o.x = pk2(s[0 * 33], s[1 * 33]); o.y = pk2(s[2 * 33], s[3 * 33]); o.z = pk2(s[4 * 33], s[5 * 33]); o.w = pk2(s[6 * 33], s[7 * 33]);
;         int rowi = n0 + n;
;         if (rowi < perm_cols) { const int oc = rowi & 255, part = oc >> 6, i6 = oc & 63; rowi = (rowi & ~255) + 128 * (part & 1) + 32 * (2 * (part >> 1) + (i6 >> 5)) + (i6 & 31); }
;         *(u32x4*)(WT + (size_t)rowi * K + k0 + 8 * c) = o; }
;     asm volatile("s_waitcnt lgkmcnt(0)" ::: "memory");
	s_waitcnt lgkmcnt(0)
	ds_read2_b32 v[26:27], v18 offset0:33 offset1:41
	ds_read2_b32 v[28:29], v18 offset1:8
	ds_read2_b32 v[30:31], v18 offset0:66 offset1:74
	ds_read2_b32 v[32:33], v18 offset0:99 offset1:107
	ds_read2_b32 v[34:35], v18 offset0:132 offset1:140
	ds_read2_b32 v[36:37], v18 offset0:165 offset1:173
	ds_read2_b32 v[38:39], v18 offset0:198 offset1:206
	ds_read2_b32 v[40:41], v18 offset0:231 offset1:239
	s_lshl_b32 s72, s17, 1
	v_or_b32_e32 v5, s16, v17
	v_lshl_add_u64 v[12:13], v[6:7], 0, s[72:73]
	v_lshlrev_b32_e32 v176, 13, v5
	v_or_b32_e32 v5, s16, v19
	s_waitcnt lgkmcnt(6)
	v_cvt_pk_bf16_f32 v22, v28, v26
	v_lshl_add_u64 v[42:43], v[12:13], 0, v[176:177]
	v_lshlrev_b32_e32 v176, 13, v5
	s_waitcnt lgkmcnt(4)
	v_cvt_pk_bf16_f32 v23, v30, v32
	s_waitcnt lgkmcnt(2)
	v_cvt_pk_bf16_f32 v24, v34, v36
	s_waitcnt lgkmcnt(0)
	v_cvt_pk_bf16_f32 v25, v38, v40
	global_store_dwordx4 v[42:43], v[22:25], off
	v_or_b32_e32 v5, s16, v20
	s_nop 0
	v_cvt_pk_bf16_f32 v22, v29, v27
	v_lshl_add_u64 v[26:27], v[12:13], 0, v[176:177]
	v_cvt_pk_bf16_f32 v23, v31, v33
	v_cvt_pk_bf16_f32 v24, v35, v37
	v_cvt_pk_bf16_f32 v25, v39, v41
	global_store_dwordx4 v[26:27], v[22:25], off
	ds_read2_b32 v[26:27], v18 offset0:16 offset1:24
	ds_read2_b32 v[28:29], v18 offset0:49 offset1:57
	ds_read2_b32 v[30:31], v18 offset0:82 offset1:90
	ds_read2_b32 v[32:33], v18 offset0:115 offset1:123
	ds_read2_b32 v[34:35], v18 offset0:148 offset1:156
	ds_read2_b32 v[36:37], v18 offset0:181 offset1:189
	ds_read2_b32 v[38:39], v18 offset0:214 offset1:222
	ds_read2_b32 v[40:41], v18 offset0:247 offset1:255
	v_lshlrev_b32_e32 v176, 13, v5
	v_or_b32_e32 v5, s16, v21
	v_lshl_add_u64 v[42:43], v[12:13], 0, v[176:177]
	v_lshlrev_b32_e32 v176, 13, v5
	s_waitcnt lgkmcnt(6)
	v_cvt_pk_bf16_f32 v22, v26, v28
	s_waitcnt lgkmcnt(4)
	v_cvt_pk_bf16_f32 v23, v30, v32
	s_waitcnt lgkmcnt(2)
	v_cvt_pk_bf16_f32 v24, v34, v36
	s_waitcnt lgkmcnt(0)
	v_cvt_pk_bf16_f32 v25, v38, v40
	v_lshl_add_u64 v[12:13], v[12:13], 0, v[176:177]
	global_store_dwordx4 v[42:43], v[22:25], off
	s_nop 1
	v_cvt_pk_bf16_f32 v22, v27, v29
	v_cvt_pk_bf16_f32 v23, v31, v33
	v_cvt_pk_bf16_f32 v24, v35, v37
	v_cvt_pk_bf16_f32 v25, v39, v41
	global_store_dwordx4 v[12:13], v[22:25], off
	s_waitcnt lgkmcnt(0)
	s_branch .LBB0_334

; #define LAS __attribute__((address_space(3)))
; __device__ __forceinline__ void transpose_item(const float* W, int K, int N, bf16_t* WT, LAS float* scr, int item, int lane, int perm_cols) {
;     const int nblk = N / 32, kb = item / nblk, nb = item % nblk, k0 = 64 * kb, n0 = 32 * nb;
; #pragma unroll 8
;     for (int i = 0; i < 32; ++i) { const int kk = 2 * i + (lane >> 5); scr[kk * 33 + (lane & 31)] = W[(size_t)(k0 + kk) * N + n0 + (lane & 31)]; }
.LBB0_341:
	s_lshl_b32 s21, s18, 1
	s_lshl_b32 s20, s17, 1
	v_or_b32_e32 v22, s21, v14
	s_waitcnt vmcnt(7)
	v_or_b32_e32 v24, s20, v5
	v_mad_i64_i32 v[22:23], s[22:23], v22, s63, v[12:13]
	v_mad_i64_i32 v[24:25], s[22:23], v24, s63, v[12:13]
	global_load_dword v80, v[22:23], off
	global_load_dword v81, v[24:25], off
	v_or_b32_e32 v26, s20, v1
	v_or_b32_e32 v27, s21, v0
	v_mad_u64_u32 v[96:97], s[22:23], v27, s60, v[4:5]
	v_mad_u64_u32 v[98:99], s[22:23], v26, s60, v[4:5]
	s_add_i32 s23, s21, 4
	s_add_i32 s22, s20, 4
	v_or_b32_e32 v26, s22, v1
	v_or_b32_e32 v27, s23, v0
	s_add_i32 s18, s18, 16
	s_add_i32 s17, s17, 16
	s_add_i32 s19, s19, -16
	v_or_b32_e32 v22, s23, v14
	v_or_b32_e32 v24, s22, v5
	v_mad_i64_i32 v[22:23], s[22:23], v22, s63, v[12:13]
	v_mad_i64_i32 v[24:25], s[22:23], v24, s63, v[12:13]
	global_load_dword v82, v[22:23], off
	global_load_dword v83, v[24:25], off
	v_mad_u64_u32 v[100:101], s[22:23], v27, s60, v[4:5]
	v_mad_u64_u32 v[102:103], s[22:23], v26, s60, v[4:5]
	s_add_i32 s23, s21, 8
	s_add_i32 s22, s20, 8
	v_or_b32_e32 v26, s22, v1
	v_or_b32_e32 v27, s23, v0
	v_or_b32_e32 v22, s23, v14
	v_or_b32_e32 v24, s22, v5
	v_mad_i64_i32 v[22:23], s[22:23], v22, s63, v[12:13]
	v_mad_i64_i32 v[24:25], s[22:23], v24, s63, v[12:13]
	global_load_dword v84, v[22:23], off
	global_load_dword v85, v[24:25], off
	v_mad_u64_u32 v[104:105], s[22:23], v27, s60, v[4:5]
	v_mad_u64_u32 v[106:107], s[22:23], v26, s60, v[4:5]
	s_add_i32 s23, s21, 12
	s_add_i32 s22, s20, 12
	v_or_b32_e32 v26, s22, v1
	v_or_b32_e32 v27, s23, v0
	v_or_b32_e32 v22, s23, v14
	v_or_b32_e32 v24, s22, v5
	v_mad_i64_i32 v[22:23], s[22:23], v22, s63, v[12:13]
	v_mad_i64_i32 v[24:25], s[22:23], v24, s63, v[12:13]
	global_load_dword v86, v[22:23], off
	global_load_dword v87, v[24:25], off
	v_mad_u64_u32 v[108:109], s[22:23], v27, s60, v[4:5]
	v_mad_u64_u32 v[110:111], s[22:23], v26, s60, v[4:5]
	s_add_i32 s23, s21, 16
	s_add_i32 s22, s20, 16
	v_or_b32_e32 v26, s22, v1
	v_or_b32_e32 v27, s23, v0
	v_or_b32_e32 v22, s23, v14
	v_or_b32_e32 v24, s22, v5
	v_mad_i64_i32 v[22:23], s[22:23], v22, s63, v[12:13]
	v_mad_i64_i32 v[24:25], s[22:23], v24, s63, v[12:13]
	global_load_dword v88, v[22:23], off
	global_load_dword v89, v[24:25], off
	v_mad_u64_u32 v[112:113], s[22:23], v27, s60, v[4:5]
	v_mad_u64_u32 v[114:115], s[22:23], v26, s60, v[4:5]
	s_add_i32 s23, s21, 20
	s_add_i32 s22, s20, 20
	v_or_b32_e32 v26, s22, v1
	v_or_b32_e32 v27, s23, v0
	v_or_b32_e32 v22, s23, v14
	v_or_b32_e32 v24, s22, v5
	v_mad_i64_i32 v[22:23], s[22:23], v22, s63, v[12:13]
	v_mad_i64_i32 v[24:25], s[22:23], v24, s63, v[12:13]
	global_load_dword v90, v[22:23], off
	global_load_dword v91, v[24:25], off
	v_mad_u64_u32 v[116:117], s[22:23], v27, s60, v[4:5]
	v_mad_u64_u32 v[118:119], s[22:23], v26, s60, v[4:5]
	s_add_i32 s23, s21, 24
	s_add_i32 s22, s20, 24
	v_or_b32_e32 v26, s22, v1
	v_or_b32_e32 v27, s23, v0
	s_add_i32 s21, s21, 28
	s_add_i32 s20, s20, 28
	s_cmp_lg_u32 s19, 0
	v_or_b32_e32 v22, s23, v14
	v_or_b32_e32 v24, s22, v5
	v_mad_i64_i32 v[22:23], s[22:23], v22, s63, v[12:13]
	v_mad_i64_i32 v[24:25], s[22:23], v24, s63, v[12:13]
	global_load_dword v92, v[22:23], off
	global_load_dword v93, v[24:25], off
	v_mad_u64_u32 v[120:121], s[22:23], v27, s60, v[4:5]
	v_mad_u64_u32 v[122:123], s[22:23], v26, s60, v[4:5]
	v_or_b32_e32 v26, s20, v1
	v_or_b32_e32 v27, s21, v0
	v_or_b32_e32 v22, s21, v14
	v_or_b32_e32 v24, s20, v5
	v_mad_i64_i32 v[22:23], s[20:21], v22, s63, v[12:13]
	v_mad_i64_i32 v[24:25], s[20:21], v24, s63, v[12:13]
	global_load_dword v94, v[22:23], off
	global_load_dword v95, v[24:25], off
	v_mad_u64_u32 v[124:125], s[20:21], v27, s60, v[4:5]
	v_mad_u64_u32 v[126:127], s[20:21], v26, s60, v[4:5]
	s_waitcnt vmcnt(15)
	ds_write_b32 v96, v80
	s_waitcnt vmcnt(14)
	ds_write_b32 v98, v81
	s_waitcnt vmcnt(13)
	ds_write_b32 v100, v82
	s_waitcnt vmcnt(12)
	ds_write_b32 v102, v83
	s_waitcnt vmcnt(11)
	ds_write_b32 v104, v84
	s_waitcnt vmcnt(10)
	ds_write_b32 v106, v85
	s_waitcnt vmcnt(9)
	ds_write_b32 v108, v86
	s_waitcnt vmcnt(8)
	ds_write_b32 v110, v87
	s_waitcnt vmcnt(7)
	ds_write_b32 v112, v88
	s_waitcnt vmcnt(6)
	ds_write_b32 v114, v89
	s_waitcnt vmcnt(5)
	ds_write_b32 v116, v90
	s_waitcnt vmcnt(4)
	ds_write_b32 v118, v91
	s_waitcnt vmcnt(3)
	ds_write_b32 v120, v92
	s_waitcnt vmcnt(2)
	ds_write_b32 v122, v93
	s_waitcnt vmcnt(1)
	ds_write_b32 v124, v94
	s_waitcnt vmcnt(0)
	ds_write_b32 v126, v95
	s_cbranch_scc1 .LBB0_341
; #define LAS __attribute__((address_space(3)))
; __device__ __forceinline__ unsigned pk2(float lo, float hi) { unsigned r; asm("v_cvt_pk_bf16_f32 %0, %1, %2" : "=v"(r) : "v"(lo), "v"(hi)); return r; }
; __device__ __forceinline__ void transpose_item(const float* W, int K, int N, bf16_t* WT, LAS float* scr, int item, int lane, int perm_cols) {
;     ...
;     asm volatile("s_waitcnt lgkmcnt(0)" ::: "memory");
;     const int c = lane & 7;
; #pragma unroll
;     for (int j = 0; j < 4; ++j) { const int n = (lane >> 3) + 8 * j; const LAS float* s = scr + (8 * c) * 33 + n;
;         u32x4 o; o.x = pk2(s[0 * 33], s[1 * 33]); o.y = pk2(s[2 * 33], s[3 * 33]); o.z = pk2(s[4 * 33], s[5 * 33]); o.w = pk2(s[6 * 33], s[7 * 33]);
;         int rowi = n0 + n;
;         if (rowi < perm_cols) { const int oc = rowi & 255, part = oc >> 6, i6 = oc & 63; rowi = (rowi & ~255) + 128 * (part & 1) + 32 * (2 * (part >> 1) + (i6 >> 5)) + (i6 & 31); }
;         *(u32x4*)(WT + (size_t)rowi * K + k0 + 8 * c) = o; }
;     asm volatile("s_waitcnt lgkmcnt(0)" ::: "memory");
	s_lshl_b32 s16, s16, 6
	s_and_b32 s16, s16, 0x80
	s_lshr_b32 s17, s40, 1
	s_and_b32 s18, s40, 0xffffff20
	s_waitcnt lgkmcnt(0)
	s_and_b32 s17, s17, 64
	s_or_b32 s16, s18, s16
	s_or_b32 s16, s16, s17
	ds_read2_b32 v[26:27], v18 offset0:33 offset1:41
	ds_read2_b32 v[28:29], v18 offset1:8
	v_or_b32_e32 v5, s40, v17
	ds_read2_b32 v[30:31], v18 offset0:66 offset1:74
	ds_read2_b32 v[32:33], v18 offset0:99 offset1:107
	ds_read2_b32 v[34:35], v18 offset0:132 offset1:140
	ds_read2_b32 v[36:37], v18 offset0:165 offset1:173
	ds_read2_b32 v[38:39], v18 offset0:198 offset1:206
	ds_read2_b32 v[40:41], v18 offset0:231 offset1:239
	v_cmp_gt_i32_e32 vcc, s47, v5
	v_or_b32_e32 v14, s16, v17
	s_ashr_i32 s45, s44, 31
	v_cndmask_b32_e32 v42, v5, v14, vcc
	v_ashrrev_i32_e32 v43, 31, v42
	v_or_b32_e32 v5, s40, v19
	v_lshl_add_u64 v[12:13], s[44:45], 1, v[10:11]
	v_lshlrev_b64 v[42:43], 12, v[42:43]
	v_cmp_gt_i32_e32 vcc, s47, v5
	v_or_b32_e32 v14, s16, v19
	s_waitcnt lgkmcnt(6)
	v_cvt_pk_bf16_f32 v22, v28, v26
	v_lshl_add_u64 v[42:43], v[12:13], 0, v[42:43]
	v_cndmask_b32_e32 v26, v5, v14, vcc
	s_waitcnt lgkmcnt(4)
	v_cvt_pk_bf16_f32 v23, v30, v32
	s_waitcnt lgkmcnt(2)
	v_cvt_pk_bf16_f32 v24, v34, v36
	s_waitcnt lgkmcnt(0)
	v_cvt_pk_bf16_f32 v25, v38, v40
	global_store_dwordx4 v[42:43], v[22:25], off
	v_or_b32_e32 v5, s40, v20
	v_cmp_gt_i32_e32 vcc, s47, v5
	v_cvt_pk_bf16_f32 v22, v29, v27
	v_ashrrev_i32_e32 v27, 31, v26
	v_lshlrev_b64 v[26:27], 12, v[26:27]
	v_lshl_add_u64 v[26:27], v[12:13], 0, v[26:27]
	v_cvt_pk_bf16_f32 v23, v31, v33
	v_cvt_pk_bf16_f32 v24, v35, v37
	v_cvt_pk_bf16_f32 v25, v39, v41
	global_store_dwordx4 v[26:27], v[22:25], off
	ds_read2_b32 v[26:27], v18 offset0:16 offset1:24
	ds_read2_b32 v[28:29], v18 offset0:49 offset1:57
	ds_read2_b32 v[30:31], v18 offset0:82 offset1:90
	ds_read2_b32 v[32:33], v18 offset0:115 offset1:123
	ds_read2_b32 v[34:35], v18 offset0:148 offset1:156
	ds_read2_b32 v[36:37], v18 offset0:181 offset1:189
	ds_read2_b32 v[38:39], v18 offset0:214 offset1:222
	ds_read2_b32 v[40:41], v18 offset0:247 offset1:255
	v_or_b32_e32 v14, s16, v20
	v_cndmask_b32_e32 v42, v5, v14, vcc
	v_ashrrev_i32_e32 v43, 31, v42
	v_or_b32_e32 v5, s40, v21
	v_lshlrev_b64 v[42:43], 12, v[42:43]
	v_cmp_gt_i32_e32 vcc, s47, v5
	v_or_b32_e32 v14, s16, v21
	s_waitcnt lgkmcnt(6)
	v_cvt_pk_bf16_f32 v22, v26, v28
	v_lshl_add_u64 v[42:43], v[12:13], 0, v[42:43]
	v_cndmask_b32_e32 v26, v5, v14, vcc
	s_waitcnt lgkmcnt(4)
	v_cvt_pk_bf16_f32 v23, v30, v32
	s_waitcnt lgkmcnt(2)
	v_cvt_pk_bf16_f32 v24, v34, v36
	s_waitcnt lgkmcnt(0)
	v_cvt_pk_bf16_f32 v25, v38, v40
	global_store_dwordx4 v[42:43], v[22:25], off
	s_nop 1
	v_cvt_pk_bf16_f32 v22, v27, v29
	v_ashrrev_i32_e32 v27, 31, v26
	v_lshlrev_b64 v[26:27], 12, v[26:27]
	v_lshl_add_u64 v[12:13], v[12:13], 0, v[26:27]
	v_cvt_pk_bf16_f32 v23, v31, v33
	v_cvt_pk_bf16_f32 v24, v35, v37
	v_cvt_pk_bf16_f32 v25, v39, v41
	global_store_dwordx4 v[12:13], v[22:25], off
	s_waitcnt lgkmcnt(0)
	s_branch .LBB0_334

; #define LAS __attribute__((address_space(3)))
; __device__ __forceinline__ void transpose_item(const float* W, int K, int N, bf16_t* WT, LAS float* scr, int item, int lane, int perm_cols) {
;     const int nblk = N / 32, kb = item / nblk, nb = item % nblk, k0 = 64 * kb, n0 = 32 * nb;
; #pragma unroll 8
;     for (int i = 0; i < 32; ++i) { const int kk = 2 * i + (lane >> 5); scr[kk * 33 + (lane & 31)] = W[(size_t)(k0 + kk) * N + n0 + (lane & 31)]; }
.LBB0_351:
	s_lshl_b32 s20, s17, 1
	s_lshl_b32 s19, s16, 1
	v_or_b32_e32 v176, s20, v14
	s_waitcnt vmcnt(8)
	v_or_b32_e32 v20, s19, v5
	v_mov_b32_e32 v21, v177
	v_lshlrev_b64 v[22:23], 13, v[176:177]
	v_lshlrev_b64 v[20:21], 13, v[20:21]
	v_lshl_add_u64 v[22:23], v[12:13], 0, v[22:23]
	v_lshl_add_u64 v[20:21], v[12:13], 0, v[20:21]
	global_load_dword v80, v[22:23], off
	global_load_dword v81, v[20:21], off
	s_waitcnt vmcnt(9)
	v_or_b32_e32 v24, s19, v1
	v_or_b32_e32 v25, s20, v0
	v_mad_u64_u32 v[96:97], s[22:23], v25, s60, v[4:5]
	v_mad_u64_u32 v[98:99], s[22:23], v24, s60, v[4:5]
	s_add_i32 s22, s20, 4
	s_add_i32 s21, s19, 4
	v_or_b32_e32 v176, s22, v14
	v_mov_b32_e32 v21, v177
	v_or_b32_e32 v24, s21, v1
	v_or_b32_e32 v25, s22, v0
	s_add_i32 s17, s17, 16
	s_add_i32 s16, s16, 16
	s_add_i32 s18, s18, -16
	v_or_b32_e32 v20, s21, v5
	v_lshlrev_b64 v[22:23], 13, v[176:177]
	v_lshlrev_b64 v[20:21], 13, v[20:21]
	v_lshl_add_u64 v[22:23], v[12:13], 0, v[22:23]
	v_lshl_add_u64 v[20:21], v[12:13], 0, v[20:21]
	global_load_dword v82, v[22:23], off
	global_load_dword v83, v[20:21], off
	v_mad_u64_u32 v[100:101], s[22:23], v25, s60, v[4:5]
	v_mad_u64_u32 v[102:103], s[22:23], v24, s60, v[4:5]
	s_add_i32 s22, s20, 8
	s_add_i32 s21, s19, 8
	v_or_b32_e32 v176, s22, v14
	v_mov_b32_e32 v21, v177
	v_or_b32_e32 v24, s21, v1
	v_or_b32_e32 v25, s22, v0
	v_or_b32_e32 v20, s21, v5
	v_lshlrev_b64 v[22:23], 13, v[176:177]
	v_lshlrev_b64 v[20:21], 13, v[20:21]
	v_lshl_add_u64 v[22:23], v[12:13], 0, v[22:23]
	v_lshl_add_u64 v[20:21], v[12:13], 0, v[20:21]
	global_load_dword v84, v[22:23], off
	global_load_dword v85, v[20:21], off
	v_mad_u64_u32 v[104:105], s[22:23], v25, s60, v[4:5]
	v_mad_u64_u32 v[106:107], s[22:23], v24, s60, v[4:5]
	s_add_i32 s22, s20, 12
	s_add_i32 s21, s19, 12
	v_or_b32_e32 v176, s22, v14
	v_mov_b32_e32 v21, v177
	v_or_b32_e32 v24, s21, v1
	v_or_b32_e32 v25, s22, v0
	v_or_b32_e32 v20, s21, v5
	v_lshlrev_b64 v[22:23], 13, v[176:177]
	v_lshlrev_b64 v[20:21], 13, v[20:21]
	v_lshl_add_u64 v[22:23], v[12:13], 0, v[22:23]
	v_lshl_add_u64 v[20:21], v[12:13], 0, v[20:21]
	global_load_dword v86, v[22:23], off
	global_load_dword v87, v[20:21], off
	v_mad_u64_u32 v[108:109], s[22:23], v25, s60, v[4:5]
	v_mad_u64_u32 v[110:111], s[22:23], v24, s60, v[4:5]
	s_add_i32 s22, s20, 16
	s_add_i32 s21, s19, 16
	v_or_b32_e32 v176, s22, v14
	v_mov_b32_e32 v21, v177
	v_or_b32_e32 v24, s21, v1
	v_or_b32_e32 v25, s22, v0
	v_or_b32_e32 v20, s21, v5
	v_lshlrev_b64 v[22:23], 13, v[176:177]
	v_lshlrev_b64 v[20:21], 13, v[20:21]
	v_lshl_add_u64 v[22:23], v[12:13], 0, v[22:23]
	v_lshl_add_u64 v[20:21], v[12:13], 0, v[20:21]
	global_load_dword v88, v[22:23], off
	global_load_dword v89, v[20:21], off
	v_mad_u64_u32 v[112:113], s[22:23], v25, s60, v[4:5]
	v_mad_u64_u32 v[114:115], s[22:23], v24, s60, v[4:5]
	s_add_i32 s22, s20, 20
	s_add_i32 s21, s19, 20
	v_or_b32_e32 v176, s22, v14
	v_mov_b32_e32 v21, v177
	v_or_b32_e32 v24, s21, v1
	v_or_b32_e32 v25, s22, v0
	v_or_b32_e32 v20, s21, v5
	v_lshlrev_b64 v[22:23], 13, v[176:177]
	v_lshlrev_b64 v[20:21], 13, v[20:21]
	v_lshl_add_u64 v[22:23], v[12:13], 0, v[22:23]
	v_lshl_add_u64 v[20:21], v[12:13], 0, v[20:21]
	global_load_dword v90, v[22:23], off
	global_load_dword v91, v[20:21], off
	v_mad_u64_u32 v[116:117], s[22:23], v25, s60, v[4:5]
	v_mad_u64_u32 v[118:119], s[22:23], v24, s60, v[4:5]
	s_add_i32 s22, s20, 24
	s_add_i32 s21, s19, 24
	v_or_b32_e32 v176, s22, v14
	v_mov_b32_e32 v21, v177
	v_or_b32_e32 v24, s21, v1
	v_or_b32_e32 v25, s22, v0
	s_add_i32 s20, s20, 28
	s_add_i32 s19, s19, 28
	s_cmp_lg_u32 s18, 0
	v_or_b32_e32 v20, s21, v5
	v_lshlrev_b64 v[22:23], 13, v[176:177]
	v_lshlrev_b64 v[20:21], 13, v[20:21]
	v_lshl_add_u64 v[22:23], v[12:13], 0, v[22:23]
	v_lshl_add_u64 v[20:21], v[12:13], 0, v[20:21]
	global_load_dword v92, v[22:23], off
	global_load_dword v93, v[20:21], off
	v_mad_u64_u32 v[120:121], s[22:23], v25, s60, v[4:5]
	v_mad_u64_u32 v[122:123], s[22:23], v24, s60, v[4:5]
	v_or_b32_e32 v176, s20, v14
	v_mov_b32_e32 v21, v177
	v_or_b32_e32 v25, s20, v0
	v_or_b32_e32 v24, s19, v1
	v_or_b32_e32 v20, s19, v5
	v_lshlrev_b64 v[22:23], 13, v[176:177]
	v_lshlrev_b64 v[20:21], 13, v[20:21]
	v_lshl_add_u64 v[22:23], v[12:13], 0, v[22:23]
	v_lshl_add_u64 v[20:21], v[12:13], 0, v[20:21]
	global_load_dword v94, v[22:23], off
	global_load_dword v95, v[20:21], off
	v_mad_u64_u32 v[124:125], s[20:21], v25, s60, v[4:5]
	v_mad_u64_u32 v[126:127], s[20:21], v24, s60, v[4:5]
	s_waitcnt vmcnt(15)
	ds_write_b32 v96, v80
	s_waitcnt vmcnt(14)
	ds_write_b32 v98, v81
	s_waitcnt vmcnt(13)
	ds_write_b32 v100, v82
	s_waitcnt vmcnt(12)
	ds_write_b32 v102, v83
	s_waitcnt vmcnt(11)
	ds_write_b32 v104, v84
	s_waitcnt vmcnt(10)
	ds_write_b32 v106, v85
	s_waitcnt vmcnt(9)
	ds_write_b32 v108, v86
	s_waitcnt vmcnt(8)
	ds_write_b32 v110, v87
	s_waitcnt vmcnt(7)
	ds_write_b32 v112, v88
	s_waitcnt vmcnt(6)
	ds_write_b32 v114, v89
	s_waitcnt vmcnt(5)
	ds_write_b32 v116, v90
	s_waitcnt vmcnt(4)
	ds_write_b32 v118, v91
	s_waitcnt vmcnt(3)
	ds_write_b32 v120, v92
	s_waitcnt vmcnt(2)
	ds_write_b32 v122, v93
	s_waitcnt vmcnt(1)
	ds_write_b32 v124, v94
	s_waitcnt vmcnt(0)
	ds_write_b32 v126, v95
	s_cbranch_scc1 .LBB0_351
; #define LAS __attribute__((address_space(3)))
; __device__ __forceinline__ unsigned pk2(float lo, float hi) { unsigned r; asm("v_cvt_pk_bf16_f32 %0, %1, %2" : "=v"(r) : "v"(lo), "v"(hi)); return r; }
; __device__ __forceinline__ void transpose_item(const float* W, int K, int N, bf16_t* WT, LAS float* scr, int item, int lane, int perm_cols) {
;     ...
;     asm volatile("s_waitcnt lgkmcnt(0)" ::: "memory");
;     const int c = lane & 7;
; #pragma unroll
;     for (int j = 0; j < 4; ++j) { const int n = (lane >> 3) + 8 * j; const LAS float* s = scr + (8 * c) * 33 + n;
;         u32x4 o; o.x = pk2(s[0 * 33], s[1 * 33]); o.y = pk2(s[2 * 33], s[3 * 33]); o.z = pk2(s[4 * 33], s[5 * 33]); o.w = pk2(s[6 * 33], s[7 * 33]);
;         int rowi = n0 + n;
;         if (rowi < perm_cols) { const int oc = rowi & 255, part = oc >> 6, i6 = oc & 63; rowi = (rowi & ~255) + 128 * (part & 1) + 32 * (2 * (part >> 1) + (i6 >> 5)) + (i6 & 31); }
;         *(u32x4*)(WT + (size_t)rowi * K + k0 + 8 * c) = o; }
;     asm volatile("s_waitcnt lgkmcnt(0)" ::: "memory");
	s_waitcnt lgkmcnt(0)
	ds_read2_b32 v[24:25], v15 offset0:33 offset1:41
	ds_read2_b32 v[26:27], v15 offset1:8
	ds_read2_b32 v[28:29], v15 offset0:66 offset1:74
	ds_read2_b32 v[30:31], v15 offset0:99 offset1:107
	ds_read2_b32 v[32:33], v15 offset0:132 offset1:140
	ds_read2_b32 v[34:35], v15 offset0:165 offset1:173
	ds_read2_b32 v[36:37], v15 offset0:198 offset1:206
	ds_read2_b32 v[38:39], v15 offset0:231 offset1:239
	s_lshl_b32 s72, s15, 1
	v_or_b32_e32 v5, s14, v16
	v_lshl_add_u64 v[12:13], v[6:7], 0, s[72:73]
	v_lshlrev_b32_e32 v176, 12, v5
	v_or_b32_e32 v5, s14, v17
	s_waitcnt lgkmcnt(6)
	v_cvt_pk_bf16_f32 v20, v26, v24
	v_lshl_add_u64 v[40:41], v[12:13], 0, v[176:177]
	v_lshlrev_b32_e32 v176, 12, v5
	s_waitcnt lgkmcnt(4)
	v_cvt_pk_bf16_f32 v21, v28, v30
	s_waitcnt lgkmcnt(2)
	v_cvt_pk_bf16_f32 v22, v32, v34
	s_waitcnt lgkmcnt(0)
	v_cvt_pk_bf16_f32 v23, v36, v38
	global_store_dwordx4 v[40:41], v[20:23], off
	v_or_b32_e32 v5, s14, v18
	s_nop 0
	v_cvt_pk_bf16_f32 v20, v27, v25
	v_lshl_add_u64 v[24:25], v[12:13], 0, v[176:177]
	v_cvt_pk_bf16_f32 v21, v29, v31
	v_cvt_pk_bf16_f32 v22, v33, v35
	v_cvt_pk_bf16_f32 v23, v37, v39
	global_store_dwordx4 v[24:25], v[20:23], off
	ds_read2_b32 v[24:25], v15 offset0:16 offset1:24
	ds_read2_b32 v[26:27], v15 offset0:49 offset1:57
	ds_read2_b32 v[28:29], v15 offset0:82 offset1:90
	ds_read2_b32 v[30:31], v15 offset0:115 offset1:123
	ds_read2_b32 v[32:33], v15 offset0:148 offset1:156
	ds_read2_b32 v[34:35], v15 offset0:181 offset1:189
	ds_read2_b32 v[36:37], v15 offset0:214 offset1:222
	ds_read2_b32 v[38:39], v15 offset0:247 offset1:255
	v_lshlrev_b32_e32 v176, 12, v5
	v_or_b32_e32 v5, s14, v19
	v_lshl_add_u64 v[40:41], v[12:13], 0, v[176:177]
	v_lshlrev_b32_e32 v176, 12, v5
	s_waitcnt lgkmcnt(6)
	v_cvt_pk_bf16_f32 v20, v24, v26
	s_waitcnt lgkmcnt(4)
	v_cvt_pk_bf16_f32 v21, v28, v30
	s_waitcnt lgkmcnt(2)
	v_cvt_pk_bf16_f32 v22, v32, v34
	s_waitcnt lgkmcnt(0)
	v_cvt_pk_bf16_f32 v23, v36, v38
	v_lshl_add_u64 v[12:13], v[12:13], 0, v[176:177]
	global_store_dwordx4 v[40:41], v[20:23], off
	s_nop 1
	v_cvt_pk_bf16_f32 v20, v25, v27
	v_cvt_pk_bf16_f32 v21, v29, v31
	v_cvt_pk_bf16_f32 v22, v33, v35
	v_cvt_pk_bf16_f32 v23, v37, v39
	global_store_dwordx4 v[12:13], v[20:23], off
	s_waitcnt lgkmcnt(0)
	s_branch .LBB0_347

; #define LAS __attribute__((address_space(3)))
; __device__ __forceinline__ void transpose_item(const float* W, int K, int N, bf16_t* WT, LAS float* scr, int item, int lane, int perm_cols) {
;     const int nblk = N / 32, kb = item / nblk, nb = item % nblk, k0 = 64 * kb, n0 = 32 * nb;
; #pragma unroll 8
;     for (int i = 0; i < 32; ++i) { const int kk = 2 * i + (lane >> 5); scr[kk * 33 + (lane & 31)] = W[(size_t)(k0 + kk) * N + n0 + (lane & 31)]; }
.LBB0_354:
	s_lshl_b32 s19, s16, 1
	s_lshl_b32 s18, s15, 1
	s_waitcnt vmcnt(8)
	v_or_b32_e32 v20, s19, v14
	v_or_b32_e32 v22, s18, v5
	v_mad_i64_i32 v[20:21], s[20:21], v20, s12, v[12:13]
	v_mad_i64_i32 v[22:23], s[20:21], v22, s12, v[12:13]
	global_load_dword v80, v[20:21], off
	global_load_dword v81, v[22:23], off
	s_waitcnt vmcnt(9)
	v_or_b32_e32 v24, s18, v1
	v_or_b32_e32 v25, s19, v0
	v_mad_u64_u32 v[96:97], s[20:21], v25, s60, v[4:5]
	v_mad_u64_u32 v[98:99], s[20:21], v24, s60, v[4:5]
	s_add_i32 s21, s19, 4
	s_add_i32 s20, s18, 4
	v_or_b32_e32 v24, s20, v1
	v_or_b32_e32 v25, s21, v0
	s_add_i32 s16, s16, 16
	s_add_i32 s15, s15, 16
	s_add_i32 s17, s17, -16
	v_or_b32_e32 v20, s21, v14
	v_or_b32_e32 v22, s20, v5
	v_mad_i64_i32 v[20:21], s[20:21], v20, s12, v[12:13]
	v_mad_i64_i32 v[22:23], s[20:21], v22, s12, v[12:13]
	global_load_dword v82, v[20:21], off
	global_load_dword v83, v[22:23], off
	v_mad_u64_u32 v[100:101], s[20:21], v25, s60, v[4:5]
	v_mad_u64_u32 v[102:103], s[20:21], v24, s60, v[4:5]
	s_add_i32 s21, s19, 8
	s_add_i32 s20, s18, 8
	v_or_b32_e32 v24, s20, v1
	v_or_b32_e32 v25, s21, v0
	v_or_b32_e32 v20, s21, v14
	v_or_b32_e32 v22, s20, v5
	v_mad_i64_i32 v[20:21], s[20:21], v20, s12, v[12:13]
	v_mad_i64_i32 v[22:23], s[20:21], v22, s12, v[12:13]
	global_load_dword v84, v[20:21], off
	global_load_dword v85, v[22:23], off
	v_mad_u64_u32 v[104:105], s[20:21], v25, s60, v[4:5]
	v_mad_u64_u32 v[106:107], s[20:21], v24, s60, v[4:5]
	s_add_i32 s21, s19, 12
	s_add_i32 s20, s18, 12
	v_or_b32_e32 v24, s20, v1
	v_or_b32_e32 v25, s21, v0
	v_or_b32_e32 v20, s21, v14
	v_or_b32_e32 v22, s20, v5
	v_mad_i64_i32 v[20:21], s[20:21], v20, s12, v[12:13]
	v_mad_i64_i32 v[22:23], s[20:21], v22, s12, v[12:13]
	global_load_dword v86, v[20:21], off
	global_load_dword v87, v[22:23], off
	v_mad_u64_u32 v[108:109], s[20:21], v25, s60, v[4:5]
	v_mad_u64_u32 v[110:111], s[20:21], v24, s60, v[4:5]
	s_add_i32 s21, s19, 16
	s_add_i32 s20, s18, 16
	v_or_b32_e32 v24, s20, v1
	v_or_b32_e32 v25, s21, v0
	v_or_b32_e32 v20, s21, v14
	v_or_b32_e32 v22, s20, v5
	v_mad_i64_i32 v[20:21], s[20:21], v20, s12, v[12:13]
	v_mad_i64_i32 v[22:23], s[20:21], v22, s12, v[12:13]
	global_load_dword v88, v[20:21], off
	global_load_dword v89, v[22:23], off
	v_mad_u64_u32 v[112:113], s[20:21], v25, s60, v[4:5]
	v_mad_u64_u32 v[114:115], s[20:21], v24, s60, v[4:5]
	s_add_i32 s21, s19, 20
	s_add_i32 s20, s18, 20
	v_or_b32_e32 v24, s20, v1
	v_or_b32_e32 v25, s21, v0
	v_or_b32_e32 v20, s21, v14
	v_or_b32_e32 v22, s20, v5
	v_mad_i64_i32 v[20:21], s[20:21], v20, s12, v[12:13]
	v_mad_i64_i32 v[22:23], s[20:21], v22, s12, v[12:13]
	global_load_dword v90, v[20:21], off
	global_load_dword v91, v[22:23], off
	v_mad_u64_u32 v[116:117], s[20:21], v25, s60, v[4:5]
	v_mad_u64_u32 v[118:119], s[20:21], v24, s60, v[4:5]
	s_add_i32 s21, s19, 24
	s_add_i32 s20, s18, 24
	v_or_b32_e32 v24, s20, v1
	v_or_b32_e32 v25, s21, v0
	s_add_i32 s19, s19, 28
	s_add_i32 s18, s18, 28
	s_cmp_lg_u32 s17, 0
	v_or_b32_e32 v20, s21, v14
	v_or_b32_e32 v22, s20, v5
	v_mad_i64_i32 v[20:21], s[20:21], v20, s12, v[12:13]
	v_mad_i64_i32 v[22:23], s[20:21], v22, s12, v[12:13]
	global_load_dword v92, v[20:21], off
	global_load_dword v93, v[22:23], off
	v_mad_u64_u32 v[120:121], s[20:21], v25, s60, v[4:5]
	v_mad_u64_u32 v[122:123], s[20:21], v24, s60, v[4:5]
	v_or_b32_e32 v24, s18, v1
	v_or_b32_e32 v25, s19, v0
	v_or_b32_e32 v20, s19, v14
	v_or_b32_e32 v22, s18, v5
	v_mad_i64_i32 v[20:21], s[18:19], v20, s12, v[12:13]
	v_mad_i64_i32 v[22:23], s[18:19], v22, s12, v[12:13]
	global_load_dword v94, v[20:21], off
	global_load_dword v95, v[22:23], off
	v_mad_u64_u32 v[124:125], s[18:19], v25, s60, v[4:5]
	v_mad_u64_u32 v[126:127], s[18:19], v24, s60, v[4:5]
	s_waitcnt vmcnt(15)
	ds_write_b32 v96, v80
	s_waitcnt vmcnt(14)
	ds_write_b32 v98, v81
	s_waitcnt vmcnt(13)
	ds_write_b32 v100, v82
	s_waitcnt vmcnt(12)
	ds_write_b32 v102, v83
	s_waitcnt vmcnt(11)
	ds_write_b32 v104, v84
	s_waitcnt vmcnt(10)
	ds_write_b32 v106, v85
	s_waitcnt vmcnt(9)
	ds_write_b32 v108, v86
	s_waitcnt vmcnt(8)
	ds_write_b32 v110, v87
	s_waitcnt vmcnt(7)
	ds_write_b32 v112, v88
	s_waitcnt vmcnt(6)
	ds_write_b32 v114, v89
	s_waitcnt vmcnt(5)
	ds_write_b32 v116, v90
	s_waitcnt vmcnt(4)
	ds_write_b32 v118, v91
	s_waitcnt vmcnt(3)
	ds_write_b32 v120, v92
	s_waitcnt vmcnt(2)
	ds_write_b32 v122, v93
	s_waitcnt vmcnt(1)
	ds_write_b32 v124, v94
	s_waitcnt vmcnt(0)
	ds_write_b32 v126, v95
	s_cbranch_scc1 .LBB0_354
; #define LAS __attribute__((address_space(3)))
; __device__ __forceinline__ unsigned pk2(float lo, float hi) { unsigned r; asm("v_cvt_pk_bf16_f32 %0, %1, %2" : "=v"(r) : "v"(lo), "v"(hi)); return r; }
; __device__ __forceinline__ void transpose_item(const float* W, int K, int N, bf16_t* WT, LAS float* scr, int item, int lane, int perm_cols) {
;     ...
;     asm volatile("s_waitcnt lgkmcnt(0)" ::: "memory");
;     const int c = lane & 7;
; #pragma unroll
;     for (int j = 0; j < 4; ++j) { const int n = (lane >> 3) + 8 * j; const LAS float* s = scr + (8 * c) * 33 + n;
;         u32x4 o; o.x = pk2(s[0 * 33], s[1 * 33]); o.y = pk2(s[2 * 33], s[3 * 33]); o.z = pk2(s[4 * 33], s[5 * 33]); o.w = pk2(s[6 * 33], s[7 * 33]);
;         int rowi = n0 + n;
;         if (rowi < perm_cols) { const int oc = rowi & 255, part = oc >> 6, i6 = oc & 63; rowi = (rowi & ~255) + 128 * (part & 1) + 32 * (2 * (part >> 1) + (i6 >> 5)) + (i6 & 31); }
;         *(u32x4*)(WT + (size_t)rowi * K + k0 + 8 * c) = o; }
;     asm volatile("s_waitcnt lgkmcnt(0)" ::: "memory");
	s_lshl_b32 s15, s14, 6
	s_and_b32 s15, s15, 0x80
	s_lshr_b32 s16, s36, 1
	s_and_b32 s17, s36, 0xffffff20
	s_and_b32 s16, s16, 64
	s_or_b32 s15, s17, s15
	s_waitcnt lgkmcnt(0)
	s_or_b32 s15, s15, s16
	s_ashr_i32 s39, s38, 31
	ds_read2_b32 v[24:25], v15 offset0:33 offset1:41
	ds_read2_b32 v[26:27], v15 offset1:8
	s_cmp_lt_i32 s14, 0
	ds_read2_b32 v[28:29], v15 offset0:66 offset1:74
	ds_read2_b32 v[30:31], v15 offset0:99 offset1:107
	ds_read2_b32 v[32:33], v15 offset0:132 offset1:140
	ds_read2_b32 v[34:35], v15 offset0:165 offset1:173
	ds_read2_b32 v[36:37], v15 offset0:198 offset1:206
	ds_read2_b32 v[38:39], v15 offset0:231 offset1:239
	s_cselect_b32 s14, s15, s36
	v_or_b32_e32 v40, s14, v16
	v_ashrrev_i32_e32 v41, 31, v40
	v_lshl_add_u64 v[12:13], s[38:39], 1, v[10:11]
	v_lshlrev_b64 v[40:41], 12, v[40:41]
	s_waitcnt lgkmcnt(6)
	v_cvt_pk_bf16_f32 v20, v26, v24
	v_lshl_add_u64 v[40:41], v[12:13], 0, v[40:41]
	v_or_b32_e32 v24, s14, v17
	s_waitcnt lgkmcnt(4)
	v_cvt_pk_bf16_f32 v21, v28, v30
	s_waitcnt lgkmcnt(2)
	v_cvt_pk_bf16_f32 v22, v32, v34
	s_waitcnt lgkmcnt(0)
	v_cvt_pk_bf16_f32 v23, v36, v38
	global_store_dwordx4 v[40:41], v[20:23], off
	v_or_b32_e32 v40, s14, v18
	v_ashrrev_i32_e32 v41, 31, v40
	v_cvt_pk_bf16_f32 v20, v27, v25
	v_ashrrev_i32_e32 v25, 31, v24
	v_lshlrev_b64 v[24:25], 12, v[24:25]
	v_lshl_add_u64 v[24:25], v[12:13], 0, v[24:25]
	v_cvt_pk_bf16_f32 v21, v29, v31
	v_cvt_pk_bf16_f32 v22, v33, v35
	v_cvt_pk_bf16_f32 v23, v37, v39
	global_store_dwordx4 v[24:25], v[20:23], off
	ds_read2_b32 v[24:25], v15 offset0:16 offset1:24
	ds_read2_b32 v[26:27], v15 offset0:49 offset1:57
	ds_read2_b32 v[28:29], v15 offset0:82 offset1:90
	ds_read2_b32 v[30:31], v15 offset0:115 offset1:123
	ds_read2_b32 v[32:33], v15 offset0:148 offset1:156
	ds_read2_b32 v[34:35], v15 offset0:181 offset1:189
	ds_read2_b32 v[36:37], v15 offset0:214 offset1:222
	ds_read2_b32 v[38:39], v15 offset0:247 offset1:255
	v_lshlrev_b64 v[40:41], 12, v[40:41]
	s_waitcnt lgkmcnt(6)
	v_cvt_pk_bf16_f32 v20, v24, v26
	v_lshl_add_u64 v[40:41], v[12:13], 0, v[40:41]
	v_or_b32_e32 v24, s14, v19
	s_waitcnt lgkmcnt(4)
	v_cvt_pk_bf16_f32 v21, v28, v30
	s_waitcnt lgkmcnt(2)
	v_cvt_pk_bf16_f32 v22, v32, v34
	s_waitcnt lgkmcnt(0)
	v_cvt_pk_bf16_f32 v23, v36, v38
	global_store_dwordx4 v[40:41], v[20:23], off
	s_nop 1
	v_cvt_pk_bf16_f32 v20, v25, v27
	v_ashrrev_i32_e32 v25, 31, v24
	v_lshlrev_b64 v[24:25], 12, v[24:25]
	v_lshl_add_u64 v[12:13], v[12:13], 0, v[24:25]
	v_cvt_pk_bf16_f32 v21, v29, v31
	v_cvt_pk_bf16_f32 v22, v33, v35
	v_cvt_pk_bf16_f32 v23, v37, v39
	global_store_dwordx4 v[12:13], v[20:23], off
	s_waitcnt lgkmcnt(0)
	s_branch .LBB0_347

; #define LAS __attribute__((address_space(3)))
; __device__ __forceinline__ void transpose_item(const float* W, int K, int N, bf16_t* WT, LAS float* scr, int item, int lane, int perm_cols) {
;     const int nblk = N / 32, kb = item / nblk, nb = item % nblk, k0 = 64 * kb, n0 = 32 * nb;
; #pragma unroll 8
;     for (int i = 0; i < 32; ++i) { const int kk = 2 * i + (lane >> 5); scr[kk * 33 + (lane & 31)] = W[(size_t)(k0 + kk) * N + n0 + (lane & 31)]; }
.LBB0_583:
	s_lshl_b32 s22, s19, 1
	s_lshl_b32 s21, s18, 1
	v_or_b32_e32 v176, s22, v14
	v_or_b32_e32 v22, s21, v5
	v_mov_b32_e32 v23, v177
	v_lshlrev_b64 v[24:25], 13, v[176:177]
	v_lshlrev_b64 v[22:23], 13, v[22:23]
	v_lshl_add_u64 v[24:25], v[12:13], 0, v[24:25]
	v_lshl_add_u64 v[22:23], v[12:13], 0, v[22:23]
	global_load_dword v80, v[24:25], off
	global_load_dword v81, v[22:23], off
	v_or_b32_e32 v26, s21, v1
	v_or_b32_e32 v27, s22, v0
	v_mad_u64_u32 v[96:97], s[24:25], v27, s60, v[4:5]
	v_mad_u64_u32 v[98:99], s[24:25], v26, s60, v[4:5]
	s_add_i32 s24, s22, 4
	s_add_i32 s23, s21, 4
	v_or_b32_e32 v176, s24, v14
	v_mov_b32_e32 v23, v177
	v_or_b32_e32 v26, s23, v1
	v_or_b32_e32 v27, s24, v0
	s_add_i32 s19, s19, 16
	s_add_i32 s18, s18, 16
	s_add_i32 s20, s20, -16
	v_or_b32_e32 v22, s23, v5
	v_lshlrev_b64 v[24:25], 13, v[176:177]
	v_lshlrev_b64 v[22:23], 13, v[22:23]
	v_lshl_add_u64 v[24:25], v[12:13], 0, v[24:25]
	v_lshl_add_u64 v[22:23], v[12:13], 0, v[22:23]
	global_load_dword v82, v[24:25], off
	global_load_dword v83, v[22:23], off
	v_mad_u64_u32 v[100:101], s[24:25], v27, s60, v[4:5]
	v_mad_u64_u32 v[102:103], s[24:25], v26, s60, v[4:5]
	s_add_i32 s24, s22, 8
	s_add_i32 s23, s21, 8
	v_or_b32_e32 v176, s24, v14
	v_mov_b32_e32 v23, v177
	v_or_b32_e32 v26, s23, v1
	v_or_b32_e32 v27, s24, v0
	v_or_b32_e32 v22, s23, v5
	v_lshlrev_b64 v[24:25], 13, v[176:177]
	v_lshlrev_b64 v[22:23], 13, v[22:23]
	v_lshl_add_u64 v[24:25], v[12:13], 0, v[24:25]
	v_lshl_add_u64 v[22:23], v[12:13], 0, v[22:23]
	global_load_dword v84, v[24:25], off
	global_load_dword v85, v[22:23], off
	v_mad_u64_u32 v[104:105], s[24:25], v27, s60, v[4:5]
	v_mad_u64_u32 v[106:107], s[24:25], v26, s60, v[4:5]
	s_add_i32 s24, s22, 12
	s_add_i32 s23, s21, 12
	v_or_b32_e32 v176, s24, v14
	v_mov_b32_e32 v23, v177
	v_or_b32_e32 v26, s23, v1
	v_or_b32_e32 v27, s24, v0
	v_or_b32_e32 v22, s23, v5
	v_lshlrev_b64 v[24:25], 13, v[176:177]
	v_lshlrev_b64 v[22:23], 13, v[22:23]
	v_lshl_add_u64 v[24:25], v[12:13], 0, v[24:25]
	v_lshl_add_u64 v[22:23], v[12:13], 0, v[22:23]
	global_load_dword v86, v[24:25], off
	global_load_dword v87, v[22:23], off
	v_mad_u64_u32 v[108:109], s[24:25], v27, s60, v[4:5]
	v_mad_u64_u32 v[110:111], s[24:25], v26, s60, v[4:5]
	s_add_i32 s24, s22, 16
	s_add_i32 s23, s21, 16
	v_or_b32_e32 v176, s24, v14
	v_mov_b32_e32 v23, v177
	v_or_b32_e32 v26, s23, v1
	v_or_b32_e32 v27, s24, v0
	v_or_b32_e32 v22, s23, v5
	v_lshlrev_b64 v[24:25], 13, v[176:177]
	v_lshlrev_b64 v[22:23], 13, v[22:23]
	v_lshl_add_u64 v[24:25], v[12:13], 0, v[24:25]
	v_lshl_add_u64 v[22:23], v[12:13], 0, v[22:23]
	global_load_dword v88, v[24:25], off
	global_load_dword v89, v[22:23], off
	v_mad_u64_u32 v[112:113], s[24:25], v27, s60, v[4:5]
	v_mad_u64_u32 v[114:115], s[24:25], v26, s60, v[4:5]
	s_add_i32 s24, s22, 20
	s_add_i32 s23, s21, 20
	v_or_b32_e32 v176, s24, v14
	v_mov_b32_e32 v23, v177
	v_or_b32_e32 v26, s23, v1
	v_or_b32_e32 v27, s24, v0
	v_or_b32_e32 v22, s23, v5
	v_lshlrev_b64 v[24:25], 13, v[176:177]
	v_lshlrev_b64 v[22:23], 13, v[22:23]
	v_lshl_add_u64 v[24:25], v[12:13], 0, v[24:25]
	v_lshl_add_u64 v[22:23], v[12:13], 0, v[22:23]
	global_load_dword v90, v[24:25], off
	global_load_dword v91, v[22:23], off
	v_mad_u64_u32 v[116:117], s[24:25], v27, s60, v[4:5]
	v_mad_u64_u32 v[118:119], s[24:25], v26, s60, v[4:5]
	s_add_i32 s24, s22, 24
	s_add_i32 s23, s21, 24
	v_or_b32_e32 v176, s24, v14
	v_mov_b32_e32 v23, v177
	v_or_b32_e32 v26, s23, v1
	v_or_b32_e32 v27, s24, v0
	s_add_i32 s22, s22, 28
	s_add_i32 s21, s21, 28
	s_cmp_lg_u32 s20, 0
	v_or_b32_e32 v22, s23, v5
	v_lshlrev_b64 v[24:25], 13, v[176:177]
	v_lshlrev_b64 v[22:23], 13, v[22:23]
	v_lshl_add_u64 v[24:25], v[12:13], 0, v[24:25]
	v_lshl_add_u64 v[22:23], v[12:13], 0, v[22:23]
	global_load_dword v92, v[24:25], off
	global_load_dword v93, v[22:23], off
	v_mad_u64_u32 v[120:121], s[24:25], v27, s60, v[4:5]
	v_mad_u64_u32 v[122:123], s[24:25], v26, s60, v[4:5]
	v_or_b32_e32 v176, s22, v14
	v_mov_b32_e32 v23, v177
	v_or_b32_e32 v27, s22, v0
	v_or_b32_e32 v26, s21, v1
	v_or_b32_e32 v22, s21, v5
	v_lshlrev_b64 v[24:25], 13, v[176:177]
	v_lshlrev_b64 v[22:23], 13, v[22:23]
	v_lshl_add_u64 v[24:25], v[12:13], 0, v[24:25]
	v_lshl_add_u64 v[22:23], v[12:13], 0, v[22:23]
	global_load_dword v94, v[24:25], off
	global_load_dword v95, v[22:23], off
	v_mad_u64_u32 v[124:125], s[22:23], v27, s60, v[4:5]
	v_mad_u64_u32 v[126:127], s[22:23], v26, s60, v[4:5]
	s_waitcnt vmcnt(15)
	ds_write_b32 v96, v80
	s_waitcnt vmcnt(14)
	ds_write_b32 v98, v81
	s_waitcnt vmcnt(13)
	ds_write_b32 v100, v82
	s_waitcnt vmcnt(12)
	ds_write_b32 v102, v83
	s_waitcnt vmcnt(11)
	ds_write_b32 v104, v84
	s_waitcnt vmcnt(10)
	ds_write_b32 v106, v85
	s_waitcnt vmcnt(9)
	ds_write_b32 v108, v86
	s_waitcnt vmcnt(8)
	ds_write_b32 v110, v87
	s_waitcnt vmcnt(7)
	ds_write_b32 v112, v88
	s_waitcnt vmcnt(6)
	ds_write_b32 v114, v89
	s_waitcnt vmcnt(5)
	ds_write_b32 v116, v90
	s_waitcnt vmcnt(4)
	ds_write_b32 v118, v91
	s_waitcnt vmcnt(3)
	ds_write_b32 v120, v92
	s_waitcnt vmcnt(2)
	ds_write_b32 v122, v93
	s_waitcnt vmcnt(1)
	ds_write_b32 v124, v94
	s_waitcnt vmcnt(0)
	ds_write_b32 v126, v95
	s_cbranch_scc1 .LBB0_583
; #define LAS __attribute__((address_space(3)))
; __device__ __forceinline__ unsigned pk2(float lo, float hi) { unsigned r; asm("v_cvt_pk_bf16_f32 %0, %1, %2" : "=v"(r) : "v"(lo), "v"(hi)); return r; }
; __device__ __forceinline__ void transpose_item(const float* W, int K, int N, bf16_t* WT, LAS float* scr, int item, int lane, int perm_cols) {
;     ...
;     asm volatile("s_waitcnt lgkmcnt(0)" ::: "memory");
;     const int c = lane & 7;
; #pragma unroll
;     for (int j = 0; j < 4; ++j) { const int n = (lane >> 3) + 8 * j; const LAS float* s = scr + (8 * c) * 33 + n;
;         u32x4 o; o.x = pk2(s[0 * 33], s[1 * 33]); o.y = pk2(s[2 * 33], s[3 * 33]); o.z = pk2(s[4 * 33], s[5 * 33]); o.w = pk2(s[6 * 33], s[7 * 33]);
;         int rowi = n0 + n;
;         if (rowi < perm_cols) { const int oc = rowi & 255, part = oc >> 6, i6 = oc & 63; rowi = (rowi & ~255) + 128 * (part & 1) + 32 * (2 * (part >> 1) + (i6 >> 5)) + (i6 & 31); }
;         *(u32x4*)(WT + (size_t)rowi * K + k0 + 8 * c) = o; }
;     asm volatile("s_waitcnt lgkmcnt(0)" ::: "memory");
	s_waitcnt lgkmcnt(0)
	ds_read2_b32 v[26:27], v18 offset0:33 offset1:41
	ds_read2_b32 v[28:29], v18 offset1:8
	ds_read2_b32 v[30:31], v18 offset0:66 offset1:74
	ds_read2_b32 v[32:33], v18 offset0:99 offset1:107
	ds_read2_b32 v[34:35], v18 offset0:132 offset1:140
	ds_read2_b32 v[36:37], v18 offset0:165 offset1:173
	ds_read2_b32 v[38:39], v18 offset0:198 offset1:206
	ds_read2_b32 v[40:41], v18 offset0:231 offset1:239
	s_lshl_b32 s72, s17, 1
	v_or_b32_e32 v5, s16, v17
	v_lshl_add_u64 v[12:13], v[6:7], 0, s[72:73]
	v_lshlrev_b32_e32 v176, 13, v5
	v_or_b32_e32 v5, s16, v19
	s_waitcnt lgkmcnt(6)
	v_cvt_pk_bf16_f32 v22, v28, v26
	v_lshl_add_u64 v[42:43], v[12:13], 0, v[176:177]
	v_lshlrev_b32_e32 v176, 13, v5
	s_waitcnt lgkmcnt(4)
	v_cvt_pk_bf16_f32 v23, v30, v32
	s_waitcnt lgkmcnt(2)
	v_cvt_pk_bf16_f32 v24, v34, v36
	s_waitcnt lgkmcnt(0)
	v_cvt_pk_bf16_f32 v25, v38, v40
	global_store_dwordx4 v[42:43], v[22:25], off
	v_or_b32_e32 v5, s16, v20
	s_nop 0
	v_cvt_pk_bf16_f32 v22, v29, v27
	v_lshl_add_u64 v[26:27], v[12:13], 0, v[176:177]
	v_cvt_pk_bf16_f32 v23, v31, v33
	v_cvt_pk_bf16_f32 v24, v35, v37
	v_cvt_pk_bf16_f32 v25, v39, v41
	global_store_dwordx4 v[26:27], v[22:25], off
	ds_read2_b32 v[26:27], v18 offset0:16 offset1:24
	ds_read2_b32 v[28:29], v18 offset0:49 offset1:57
	ds_read2_b32 v[30:31], v18 offset0:82 offset1:90
	ds_read2_b32 v[32:33], v18 offset0:115 offset1:123
	ds_read2_b32 v[34:35], v18 offset0:148 offset1:156
	ds_read2_b32 v[36:37], v18 offset0:181 offset1:189
	ds_read2_b32 v[38:39], v18 offset0:214 offset1:222
	ds_read2_b32 v[40:41], v18 offset0:247 offset1:255
	v_lshlrev_b32_e32 v176, 13, v5
	v_or_b32_e32 v5, s16, v21
	v_lshl_add_u64 v[42:43], v[12:13], 0, v[176:177]
	v_lshlrev_b32_e32 v176, 13, v5
	s_waitcnt lgkmcnt(6)
	v_cvt_pk_bf16_f32 v22, v26, v28
	s_waitcnt lgkmcnt(4)
	v_cvt_pk_bf16_f32 v23, v30, v32
	s_waitcnt lgkmcnt(2)
	v_cvt_pk_bf16_f32 v24, v34, v36
	s_waitcnt lgkmcnt(0)
	v_cvt_pk_bf16_f32 v25, v38, v40
	v_lshl_add_u64 v[12:13], v[12:13], 0, v[176:177]
	global_store_dwordx4 v[42:43], v[22:25], off
	s_nop 1
	v_cvt_pk_bf16_f32 v22, v27, v29
	v_cvt_pk_bf16_f32 v23, v31, v33
	v_cvt_pk_bf16_f32 v24, v35, v37
	v_cvt_pk_bf16_f32 v25, v39, v41
	global_store_dwordx4 v[12:13], v[22:25], off
	s_waitcnt lgkmcnt(0)
	s_branch .LBB0_579

; #define LAS __attribute__((address_space(3)))
; __device__ __forceinline__ void transpose_item(const float* W, int K, int N, bf16_t* WT, LAS float* scr, int item, int lane, int perm_cols) {
;     const int nblk = N / 32, kb = item / nblk, nb = item % nblk, k0 = 64 * kb, n0 = 32 * nb;
; #pragma unroll 8
;     for (int i = 0; i < 32; ++i) { const int kk = 2 * i + (lane >> 5); scr[kk * 33 + (lane & 31)] = W[(size_t)(k0 + kk) * N + n0 + (lane & 31)]; }
.LBB0_586:
	s_lshl_b32 s21, s18, 1
	s_lshl_b32 s20, s17, 1
	v_or_b32_e32 v22, s21, v14
	v_or_b32_e32 v24, s20, v5
	v_mad_i64_i32 v[22:23], s[22:23], v22, s63, v[12:13]
	v_mad_i64_i32 v[24:25], s[22:23], v24, s63, v[12:13]
	global_load_dword v80, v[22:23], off
	global_load_dword v81, v[24:25], off
	v_or_b32_e32 v26, s20, v1
	v_or_b32_e32 v27, s21, v0
	v_mad_u64_u32 v[96:97], s[22:23], v27, s60, v[4:5]
	v_mad_u64_u32 v[98:99], s[22:23], v26, s60, v[4:5]
	s_add_i32 s23, s21, 4
	s_add_i32 s22, s20, 4
	v_or_b32_e32 v26, s22, v1
	v_or_b32_e32 v27, s23, v0
	s_add_i32 s18, s18, 16
	s_add_i32 s17, s17, 16
	s_add_i32 s19, s19, -16
	v_or_b32_e32 v22, s23, v14
	v_or_b32_e32 v24, s22, v5
	v_mad_i64_i32 v[22:23], s[22:23], v22, s63, v[12:13]
	v_mad_i64_i32 v[24:25], s[22:23], v24, s63, v[12:13]
	global_load_dword v82, v[22:23], off
	global_load_dword v83, v[24:25], off
	v_mad_u64_u32 v[100:101], s[22:23], v27, s60, v[4:5]
	v_mad_u64_u32 v[102:103], s[22:23], v26, s60, v[4:5]
	s_add_i32 s23, s21, 8
	s_add_i32 s22, s20, 8
	v_or_b32_e32 v26, s22, v1
	v_or_b32_e32 v27, s23, v0
	v_or_b32_e32 v22, s23, v14
	v_or_b32_e32 v24, s22, v5
	v_mad_i64_i32 v[22:23], s[22:23], v22, s63, v[12:13]
	v_mad_i64_i32 v[24:25], s[22:23], v24, s63, v[12:13]
	global_load_dword v84, v[22:23], off
	global_load_dword v85, v[24:25], off
	v_mad_u64_u32 v[104:105], s[22:23], v27, s60, v[4:5]
	v_mad_u64_u32 v[106:107], s[22:23], v26, s60, v[4:5]
	s_add_i32 s23, s21, 12
	s_add_i32 s22, s20, 12
	v_or_b32_e32 v26, s22, v1
	v_or_b32_e32 v27, s23, v0
	v_or_b32_e32 v22, s23, v14
	v_or_b32_e32 v24, s22, v5
	v_mad_i64_i32 v[22:23], s[22:23], v22, s63, v[12:13]
	v_mad_i64_i32 v[24:25], s[22:23], v24, s63, v[12:13]
	global_load_dword v86, v[22:23], off
	global_load_dword v87, v[24:25], off
	v_mad_u64_u32 v[108:109], s[22:23], v27, s60, v[4:5]
	v_mad_u64_u32 v[110:111], s[22:23], v26, s60, v[4:5]
	s_add_i32 s23, s21, 16
	s_add_i32 s22, s20, 16
	v_or_b32_e32 v26, s22, v1
	v_or_b32_e32 v27, s23, v0
	v_or_b32_e32 v22, s23, v14
	v_or_b32_e32 v24, s22, v5
	v_mad_i64_i32 v[22:23], s[22:23], v22, s63, v[12:13]
	v_mad_i64_i32 v[24:25], s[22:23], v24, s63, v[12:13]
	global_load_dword v88, v[22:23], off
	global_load_dword v89, v[24:25], off
	v_mad_u64_u32 v[112:113], s[22:23], v27, s60, v[4:5]
	v_mad_u64_u32 v[114:115], s[22:23], v26, s60, v[4:5]
	s_add_i32 s23, s21, 20
	s_add_i32 s22, s20, 20
	v_or_b32_e32 v26, s22, v1
	v_or_b32_e32 v27, s23, v0
	v_or_b32_e32 v22, s23, v14
	v_or_b32_e32 v24, s22, v5
	v_mad_i64_i32 v[22:23], s[22:23], v22, s63, v[12:13]
	v_mad_i64_i32 v[24:25], s[22:23], v24, s63, v[12:13]
	global_load_dword v90, v[22:23], off
	global_load_dword v91, v[24:25], off
	v_mad_u64_u32 v[116:117], s[22:23], v27, s60, v[4:5]
	v_mad_u64_u32 v[118:119], s[22:23], v26, s60, v[4:5]
	s_add_i32 s23, s21, 24
	s_add_i32 s22, s20, 24
	v_or_b32_e32 v26, s22, v1
	v_or_b32_e32 v27, s23, v0
	s_add_i32 s21, s21, 28
	s_add_i32 s20, s20, 28
	s_cmp_lg_u32 s19, 0
	v_or_b32_e32 v22, s23, v14
	v_or_b32_e32 v24, s22, v5
	v_mad_i64_i32 v[22:23], s[22:23], v22, s63, v[12:13]
	v_mad_i64_i32 v[24:25], s[22:23], v24, s63, v[12:13]
	global_load_dword v92, v[22:23], off
	global_load_dword v93, v[24:25], off
	v_mad_u64_u32 v[120:121], s[22:23], v27, s60, v[4:5]
	v_mad_u64_u32 v[122:123], s[22:23], v26, s60, v[4:5]
	v_or_b32_e32 v26, s20, v1
	v_or_b32_e32 v27, s21, v0
	v_or_b32_e32 v22, s21, v14
	v_or_b32_e32 v24, s20, v5
	v_mad_i64_i32 v[22:23], s[20:21], v22, s63, v[12:13]
	v_mad_i64_i32 v[24:25], s[20:21], v24, s63, v[12:13]
	global_load_dword v94, v[22:23], off
	global_load_dword v95, v[24:25], off
	v_mad_u64_u32 v[124:125], s[20:21], v27, s60, v[4:5]
	v_mad_u64_u32 v[126:127], s[20:21], v26, s60, v[4:5]
	s_waitcnt vmcnt(15)
	ds_write_b32 v96, v80
	s_waitcnt vmcnt(14)
	ds_write_b32 v98, v81
	s_waitcnt vmcnt(13)
	ds_write_b32 v100, v82
	s_waitcnt vmcnt(12)
	ds_write_b32 v102, v83
	s_waitcnt vmcnt(11)
	ds_write_b32 v104, v84
	s_waitcnt vmcnt(10)
	ds_write_b32 v106, v85
	s_waitcnt vmcnt(9)
	ds_write_b32 v108, v86
	s_waitcnt vmcnt(8)
	ds_write_b32 v110, v87
	s_waitcnt vmcnt(7)
	ds_write_b32 v112, v88
	s_waitcnt vmcnt(6)
	ds_write_b32 v114, v89
	s_waitcnt vmcnt(5)
	ds_write_b32 v116, v90
	s_waitcnt vmcnt(4)
	ds_write_b32 v118, v91
	s_waitcnt vmcnt(3)
	ds_write_b32 v120, v92
	s_waitcnt vmcnt(2)
	ds_write_b32 v122, v93
	s_waitcnt vmcnt(1)
	ds_write_b32 v124, v94
	s_waitcnt vmcnt(0)
	ds_write_b32 v126, v95
	s_cbranch_scc1 .LBB0_586
; #define LAS __attribute__((address_space(3)))
; __device__ __forceinline__ unsigned pk2(float lo, float hi) { unsigned r; asm("v_cvt_pk_bf16_f32 %0, %1, %2" : "=v"(r) : "v"(lo), "v"(hi)); return r; }
; __device__ __forceinline__ void transpose_item(const float* W, int K, int N, bf16_t* WT, LAS float* scr, int item, int lane, int perm_cols) {
;     ...
;     asm volatile("s_waitcnt lgkmcnt(0)" ::: "memory");
;     const int c = lane & 7;
; #pragma unroll
;     for (int j = 0; j < 4; ++j) { const int n = (lane >> 3) + 8 * j; const LAS float* s = scr + (8 * c) * 33 + n;
;         u32x4 o; o.x = pk2(s[0 * 33], s[1 * 33]); o.y = pk2(s[2 * 33], s[3 * 33]); o.z = pk2(s[4 * 33], s[5 * 33]); o.w = pk2(s[6 * 33], s[7 * 33]);
;         int rowi = n0 + n;
;         if (rowi < perm_cols) { const int oc = rowi & 255, part = oc >> 6, i6 = oc & 63; rowi = (rowi & ~255) + 128 * (part & 1) + 32 * (2 * (part >> 1) + (i6 >> 5)) + (i6 & 31); }
;         *(u32x4*)(WT + (size_t)rowi * K + k0 + 8 * c) = o; }
;     asm volatile("s_waitcnt lgkmcnt(0)" ::: "memory");
	s_lshl_b32 s16, s16, 6
	s_and_b32 s16, s16, 0x80
	s_lshr_b32 s17, s40, 1
	s_and_b32 s18, s40, 0xffffff20
	s_waitcnt lgkmcnt(0)
	s_and_b32 s17, s17, 64
	s_or_b32 s16, s18, s16
	s_or_b32 s16, s16, s17
	ds_read2_b32 v[26:27], v18 offset0:33 offset1:41
	ds_read2_b32 v[28:29], v18 offset1:8
	v_or_b32_e32 v5, s40, v17
	ds_read2_b32 v[30:31], v18 offset0:66 offset1:74
	ds_read2_b32 v[32:33], v18 offset0:99 offset1:107
	ds_read2_b32 v[34:35], v18 offset0:132 offset1:140
	ds_read2_b32 v[36:37], v18 offset0:165 offset1:173
	ds_read2_b32 v[38:39], v18 offset0:198 offset1:206
	ds_read2_b32 v[40:41], v18 offset0:231 offset1:239
	v_cmp_gt_i32_e32 vcc, s47, v5
	v_or_b32_e32 v14, s16, v17
	s_ashr_i32 s45, s44, 31
	v_cndmask_b32_e32 v42, v5, v14, vcc
	v_ashrrev_i32_e32 v43, 31, v42
	v_or_b32_e32 v5, s40, v19
	v_lshl_add_u64 v[12:13], s[44:45], 1, v[10:11]
	v_lshlrev_b64 v[42:43], 12, v[42:43]
	v_cmp_gt_i32_e32 vcc, s47, v5
	v_or_b32_e32 v14, s16, v19
	s_waitcnt lgkmcnt(6)
	v_cvt_pk_bf16_f32 v22, v28, v26
	v_lshl_add_u64 v[42:43], v[12:13], 0, v[42:43]
	v_cndmask_b32_e32 v26, v5, v14, vcc
	s_waitcnt lgkmcnt(4)
	v_cvt_pk_bf16_f32 v23, v30, v32
	s_waitcnt lgkmcnt(2)
	v_cvt_pk_bf16_f32 v24, v34, v36
	s_waitcnt lgkmcnt(0)
	v_cvt_pk_bf16_f32 v25, v38, v40
	global_store_dwordx4 v[42:43], v[22:25], off
	v_or_b32_e32 v5, s40, v20
	v_cmp_gt_i32_e32 vcc, s47, v5
	v_cvt_pk_bf16_f32 v22, v29, v27
	v_ashrrev_i32_e32 v27, 31, v26
	v_lshlrev_b64 v[26:27], 12, v[26:27]
	v_lshl_add_u64 v[26:27], v[12:13], 0, v[26:27]
	v_cvt_pk_bf16_f32 v23, v31, v33
	v_cvt_pk_bf16_f32 v24, v35, v37
	v_cvt_pk_bf16_f32 v25, v39, v41
	global_store_dwordx4 v[26:27], v[22:25], off
	ds_read2_b32 v[26:27], v18 offset0:16 offset1:24
	ds_read2_b32 v[28:29], v18 offset0:49 offset1:57
	ds_read2_b32 v[30:31], v18 offset0:82 offset1:90
	ds_read2_b32 v[32:33], v18 offset0:115 offset1:123
	ds_read2_b32 v[34:35], v18 offset0:148 offset1:156
	ds_read2_b32 v[36:37], v18 offset0:181 offset1:189
	ds_read2_b32 v[38:39], v18 offset0:214 offset1:222
	ds_read2_b32 v[40:41], v18 offset0:247 offset1:255
	v_or_b32_e32 v14, s16, v20
	v_cndmask_b32_e32 v42, v5, v14, vcc
	v_ashrrev_i32_e32 v43, 31, v42
	v_or_b32_e32 v5, s40, v21
	v_lshlrev_b64 v[42:43], 12, v[42:43]
	v_cmp_gt_i32_e32 vcc, s47, v5
	v_or_b32_e32 v14, s16, v21
	s_waitcnt lgkmcnt(6)
	v_cvt_pk_bf16_f32 v22, v26, v28
	v_lshl_add_u64 v[42:43], v[12:13], 0, v[42:43]
	v_cndmask_b32_e32 v26, v5, v14, vcc
	s_waitcnt lgkmcnt(4)
	v_cvt_pk_bf16_f32 v23, v30, v32
	s_waitcnt lgkmcnt(2)
	v_cvt_pk_bf16_f32 v24, v34, v36
	s_waitcnt lgkmcnt(0)
	v_cvt_pk_bf16_f32 v25, v38, v40
	global_store_dwordx4 v[42:43], v[22:25], off
	s_nop 1
	v_cvt_pk_bf16_f32 v22, v27, v29
	v_ashrrev_i32_e32 v27, 31, v26
	v_lshlrev_b64 v[26:27], 12, v[26:27]
	v_lshl_add_u64 v[12:13], v[12:13], 0, v[26:27]
	v_cvt_pk_bf16_f32 v23, v31, v33
	v_cvt_pk_bf16_f32 v24, v35, v37
	v_cvt_pk_bf16_f32 v25, v39, v41
	global_store_dwordx4 v[12:13], v[22:25], off
	s_waitcnt lgkmcnt(0)
	s_branch .LBB0_579

; #define LAS __attribute__((address_space(3)))
; __device__ __forceinline__ void transpose_item(const float* W, int K, int N, bf16_t* WT, LAS float* scr, int item, int lane, int perm_cols) {
;     const int nblk = N / 32, kb = item / nblk, nb = item % nblk, k0 = 64 * kb, n0 = 32 * nb;
; #pragma unroll 8
;     for (int i = 0; i < 32; ++i) { const int kk = 2 * i + (lane >> 5); scr[kk * 33 + (lane & 31)] = W[(size_t)(k0 + kk) * N + n0 + (lane & 31)]; }
.LBB0_596:
	s_lshl_b32 s20, s17, 1
	s_lshl_b32 s19, s16, 1
	v_or_b32_e32 v176, s20, v14
	v_or_b32_e32 v20, s19, v5
	v_mov_b32_e32 v21, v177
	v_lshlrev_b64 v[22:23], 13, v[176:177]
	v_lshlrev_b64 v[20:21], 13, v[20:21]
	v_lshl_add_u64 v[22:23], v[12:13], 0, v[22:23]
	v_lshl_add_u64 v[20:21], v[12:13], 0, v[20:21]
	global_load_dword v80, v[22:23], off
	global_load_dword v81, v[20:21], off
	v_or_b32_e32 v24, s19, v1
	v_or_b32_e32 v25, s20, v0
	v_mad_u64_u32 v[96:97], s[22:23], v25, s60, v[4:5]
	v_mad_u64_u32 v[98:99], s[22:23], v24, s60, v[4:5]
	s_add_i32 s22, s20, 4
	s_add_i32 s21, s19, 4
	v_or_b32_e32 v176, s22, v14
	v_mov_b32_e32 v21, v177
	v_or_b32_e32 v24, s21, v1
	v_or_b32_e32 v25, s22, v0
	s_add_i32 s17, s17, 16
	s_add_i32 s16, s16, 16
	s_add_i32 s18, s18, -16
	v_or_b32_e32 v20, s21, v5
	v_lshlrev_b64 v[22:23], 13, v[176:177]
	v_lshlrev_b64 v[20:21], 13, v[20:21]
	v_lshl_add_u64 v[22:23], v[12:13], 0, v[22:23]
	v_lshl_add_u64 v[20:21], v[12:13], 0, v[20:21]
	global_load_dword v82, v[22:23], off
	global_load_dword v83, v[20:21], off
	v_mad_u64_u32 v[100:101], s[22:23], v25, s60, v[4:5]
	v_mad_u64_u32 v[102:103], s[22:23], v24, s60, v[4:5]
	s_add_i32 s22, s20, 8
	s_add_i32 s21, s19, 8
	v_or_b32_e32 v176, s22, v14
	v_mov_b32_e32 v21, v177
	v_or_b32_e32 v24, s21, v1
	v_or_b32_e32 v25, s22, v0
	v_or_b32_e32 v20, s21, v5
	v_lshlrev_b64 v[22:23], 13, v[176:177]
	v_lshlrev_b64 v[20:21], 13, v[20:21]
	v_lshl_add_u64 v[22:23], v[12:13], 0, v[22:23]
	v_lshl_add_u64 v[20:21], v[12:13], 0, v[20:21]
	global_load_dword v84, v[22:23], off
	global_load_dword v85, v[20:21], off
	v_mad_u64_u32 v[104:105], s[22:23], v25, s60, v[4:5]
	v_mad_u64_u32 v[106:107], s[22:23], v24, s60, v[4:5]
	s_add_i32 s22, s20, 12
	s_add_i32 s21, s19, 12
	v_or_b32_e32 v176, s22, v14
	v_mov_b32_e32 v21, v177
	v_or_b32_e32 v24, s21, v1
	v_or_b32_e32 v25, s22, v0
	v_or_b32_e32 v20, s21, v5
	v_lshlrev_b64 v[22:23], 13, v[176:177]
	v_lshlrev_b64 v[20:21], 13, v[20:21]
	v_lshl_add_u64 v[22:23], v[12:13], 0, v[22:23]
	v_lshl_add_u64 v[20:21], v[12:13], 0, v[20:21]
	global_load_dword v86, v[22:23], off
	global_load_dword v87, v[20:21], off
	v_mad_u64_u32 v[108:109], s[22:23], v25, s60, v[4:5]
	v_mad_u64_u32 v[110:111], s[22:23], v24, s60, v[4:5]
	s_add_i32 s22, s20, 16
	s_add_i32 s21, s19, 16
	v_or_b32_e32 v176, s22, v14
	v_mov_b32_e32 v21, v177
	v_or_b32_e32 v24, s21, v1
	v_or_b32_e32 v25, s22, v0
	v_or_b32_e32 v20, s21, v5
	v_lshlrev_b64 v[22:23], 13, v[176:177]
	v_lshlrev_b64 v[20:21], 13, v[20:21]
	v_lshl_add_u64 v[22:23], v[12:13], 0, v[22:23]
	v_lshl_add_u64 v[20:21], v[12:13], 0, v[20:21]
	global_load_dword v88, v[22:23], off
	global_load_dword v89, v[20:21], off
	v_mad_u64_u32 v[112:113], s[22:23], v25, s60, v[4:5]
	v_mad_u64_u32 v[114:115], s[22:23], v24, s60, v[4:5]
	s_add_i32 s22, s20, 20
	s_add_i32 s21, s19, 20
	v_or_b32_e32 v176, s22, v14
	v_mov_b32_e32 v21, v177
	v_or_b32_e32 v24, s21, v1
	v_or_b32_e32 v25, s22, v0
	v_or_b32_e32 v20, s21, v5
	v_lshlrev_b64 v[22:23], 13, v[176:177]
	v_lshlrev_b64 v[20:21], 13, v[20:21]
	v_lshl_add_u64 v[22:23], v[12:13], 0, v[22:23]
	v_lshl_add_u64 v[20:21], v[12:13], 0, v[20:21]
	global_load_dword v90, v[22:23], off
	global_load_dword v91, v[20:21], off
	v_mad_u64_u32 v[116:117], s[22:23], v25, s60, v[4:5]
	v_mad_u64_u32 v[118:119], s[22:23], v24, s60, v[4:5]
	s_add_i32 s22, s20, 24
	s_add_i32 s21, s19, 24
	v_or_b32_e32 v176, s22, v14
	v_mov_b32_e32 v21, v177
	v_or_b32_e32 v24, s21, v1
	v_or_b32_e32 v25, s22, v0
	s_add_i32 s20, s20, 28
	s_add_i32 s19, s19, 28
	s_cmp_lg_u32 s18, 0
	v_or_b32_e32 v20, s21, v5
	v_lshlrev_b64 v[22:23], 13, v[176:177]
	v_lshlrev_b64 v[20:21], 13, v[20:21]
	v_lshl_add_u64 v[22:23], v[12:13], 0, v[22:23]
	v_lshl_add_u64 v[20:21], v[12:13], 0, v[20:21]
	global_load_dword v92, v[22:23], off
	global_load_dword v93, v[20:21], off
	v_mad_u64_u32 v[120:121], s[22:23], v25, s60, v[4:5]
	v_mad_u64_u32 v[122:123], s[22:23], v24, s60, v[4:5]
	v_or_b32_e32 v176, s20, v14
	v_mov_b32_e32 v21, v177
	v_or_b32_e32 v25, s20, v0
	v_or_b32_e32 v24, s19, v1
	v_or_b32_e32 v20, s19, v5
	v_lshlrev_b64 v[22:23], 13, v[176:177]
	v_lshlrev_b64 v[20:21], 13, v[20:21]
	v_lshl_add_u64 v[22:23], v[12:13], 0, v[22:23]
	v_lshl_add_u64 v[20:21], v[12:13], 0, v[20:21]
	global_load_dword v94, v[22:23], off
	global_load_dword v95, v[20:21], off
	v_mad_u64_u32 v[124:125], s[20:21], v25, s60, v[4:5]
	v_mad_u64_u32 v[126:127], s[20:21], v24, s60, v[4:5]
	s_waitcnt vmcnt(15)
	ds_write_b32 v96, v80
	s_waitcnt vmcnt(14)
	ds_write_b32 v98, v81
	s_waitcnt vmcnt(13)
	ds_write_b32 v100, v82
	s_waitcnt vmcnt(12)
	ds_write_b32 v102, v83
	s_waitcnt vmcnt(11)
	ds_write_b32 v104, v84
	s_waitcnt vmcnt(10)
	ds_write_b32 v106, v85
	s_waitcnt vmcnt(9)
	ds_write_b32 v108, v86
	s_waitcnt vmcnt(8)
	ds_write_b32 v110, v87
	s_waitcnt vmcnt(7)
	ds_write_b32 v112, v88
	s_waitcnt vmcnt(6)
	ds_write_b32 v114, v89
	s_waitcnt vmcnt(5)
	ds_write_b32 v116, v90
	s_waitcnt vmcnt(4)
	ds_write_b32 v118, v91
	s_waitcnt vmcnt(3)
	ds_write_b32 v120, v92
	s_waitcnt vmcnt(2)
	ds_write_b32 v122, v93
	s_waitcnt vmcnt(1)
	ds_write_b32 v124, v94
	s_waitcnt vmcnt(0)
	ds_write_b32 v126, v95
	s_cbranch_scc1 .LBB0_596
; #define LAS __attribute__((address_space(3)))
; __device__ __forceinline__ unsigned pk2(float lo, float hi) { unsigned r; asm("v_cvt_pk_bf16_f32 %0, %1, %2" : "=v"(r) : "v"(lo), "v"(hi)); return r; }
; __device__ __forceinline__ void transpose_item(const float* W, int K, int N, bf16_t* WT, LAS float* scr, int item, int lane, int perm_cols) {
;     ...
;     asm volatile("s_waitcnt lgkmcnt(0)" ::: "memory");
;     const int c = lane & 7;
; #pragma unroll
;     for (int j = 0; j < 4; ++j) { const int n = (lane >> 3) + 8 * j; const LAS float* s = scr + (8 * c) * 33 + n;
;         u32x4 o; o.x = pk2(s[0 * 33], s[1 * 33]); o.y = pk2(s[2 * 33], s[3 * 33]); o.z = pk2(s[4 * 33], s[5 * 33]); o.w = pk2(s[6 * 33], s[7 * 33]);
;         int rowi = n0 + n;
;         if (rowi < perm_cols) { const int oc = rowi & 255, part = oc >> 6, i6 = oc & 63; rowi = (rowi & ~255) + 128 * (part & 1) + 32 * (2 * (part >> 1) + (i6 >> 5)) + (i6 & 31); }
;         *(u32x4*)(WT + (size_t)rowi * K + k0 + 8 * c) = o; }
;     asm volatile("s_waitcnt lgkmcnt(0)" ::: "memory");
	s_waitcnt lgkmcnt(0)
	ds_read2_b32 v[24:25], v15 offset0:33 offset1:41
	ds_read2_b32 v[26:27], v15 offset1:8
	ds_read2_b32 v[28:29], v15 offset0:66 offset1:74
	ds_read2_b32 v[30:31], v15 offset0:99 offset1:107
	ds_read2_b32 v[32:33], v15 offset0:132 offset1:140
	ds_read2_b32 v[34:35], v15 offset0:165 offset1:173
	ds_read2_b32 v[36:37], v15 offset0:198 offset1:206
	ds_read2_b32 v[38:39], v15 offset0:231 offset1:239
	s_lshl_b32 s72, s15, 1
	v_or_b32_e32 v5, s14, v16
	v_lshl_add_u64 v[12:13], v[6:7], 0, s[72:73]
	v_lshlrev_b32_e32 v176, 12, v5
	v_or_b32_e32 v5, s14, v17
	s_waitcnt lgkmcnt(6)
	v_cvt_pk_bf16_f32 v20, v26, v24
	v_lshl_add_u64 v[40:41], v[12:13], 0, v[176:177]
	v_lshlrev_b32_e32 v176, 12, v5
	s_waitcnt lgkmcnt(4)
	v_cvt_pk_bf16_f32 v21, v28, v30
	s_waitcnt lgkmcnt(2)
	v_cvt_pk_bf16_f32 v22, v32, v34
	s_waitcnt lgkmcnt(0)
	v_cvt_pk_bf16_f32 v23, v36, v38
	global_store_dwordx4 v[40:41], v[20:23], off
	v_or_b32_e32 v5, s14, v18
	s_nop 0
	v_cvt_pk_bf16_f32 v20, v27, v25
	v_lshl_add_u64 v[24:25], v[12:13], 0, v[176:177]
	v_cvt_pk_bf16_f32 v21, v29, v31
	v_cvt_pk_bf16_f32 v22, v33, v35
	v_cvt_pk_bf16_f32 v23, v37, v39
	global_store_dwordx4 v[24:25], v[20:23], off
	ds_read2_b32 v[24:25], v15 offset0:16 offset1:24
	ds_read2_b32 v[26:27], v15 offset0:49 offset1:57
	ds_read2_b32 v[28:29], v15 offset0:82 offset1:90
	ds_read2_b32 v[30:31], v15 offset0:115 offset1:123
	ds_read2_b32 v[32:33], v15 offset0:148 offset1:156
	ds_read2_b32 v[34:35], v15 offset0:181 offset1:189
	ds_read2_b32 v[36:37], v15 offset0:214 offset1:222
	ds_read2_b32 v[38:39], v15 offset0:247 offset1:255
	v_lshlrev_b32_e32 v176, 12, v5
	v_or_b32_e32 v5, s14, v19
	v_lshl_add_u64 v[40:41], v[12:13], 0, v[176:177]
	v_lshlrev_b32_e32 v176, 12, v5
	s_waitcnt lgkmcnt(6)
	v_cvt_pk_bf16_f32 v20, v24, v26
	s_waitcnt lgkmcnt(4)
	v_cvt_pk_bf16_f32 v21, v28, v30
	s_waitcnt lgkmcnt(2)
	v_cvt_pk_bf16_f32 v22, v32, v34
	s_waitcnt lgkmcnt(0)
	v_cvt_pk_bf16_f32 v23, v36, v38
	v_lshl_add_u64 v[12:13], v[12:13], 0, v[176:177]
	global_store_dwordx4 v[40:41], v[20:23], off
	s_nop 1
	v_cvt_pk_bf16_f32 v20, v25, v27
	v_cvt_pk_bf16_f32 v21, v29, v31
	v_cvt_pk_bf16_f32 v22, v33, v35
	v_cvt_pk_bf16_f32 v23, v37, v39
	global_store_dwordx4 v[12:13], v[20:23], off
	s_waitcnt lgkmcnt(0)
	s_branch .LBB0_592

; #define LAS __attribute__((address_space(3)))
; __device__ __forceinline__ void transpose_item(const float* W, int K, int N, bf16_t* WT, LAS float* scr, int item, int lane, int perm_cols) {
;     const int nblk = N / 32, kb = item / nblk, nb = item % nblk, k0 = 64 * kb, n0 = 32 * nb;
; #pragma unroll 8
;     for (int i = 0; i < 32; ++i) { const int kk = 2 * i + (lane >> 5); scr[kk * 33 + (lane & 31)] = W[(size_t)(k0 + kk) * N + n0 + (lane & 31)]; }
.LBB0_599:
	s_lshl_b32 s19, s16, 1
	s_lshl_b32 s18, s15, 1
	v_or_b32_e32 v20, s19, v14
	v_or_b32_e32 v22, s18, v5
	v_mad_i64_i32 v[20:21], s[20:21], v20, s12, v[12:13]
	v_mad_i64_i32 v[22:23], s[20:21], v22, s12, v[12:13]
	global_load_dword v80, v[20:21], off
	global_load_dword v81, v[22:23], off
	v_or_b32_e32 v24, s18, v1
	v_or_b32_e32 v25, s19, v0
	v_mad_u64_u32 v[96:97], s[20:21], v25, s60, v[4:5]
	v_mad_u64_u32 v[98:99], s[20:21], v24, s60, v[4:5]
	s_add_i32 s21, s19, 4
	s_add_i32 s20, s18, 4
	v_or_b32_e32 v24, s20, v1
	v_or_b32_e32 v25, s21, v0
	s_add_i32 s16, s16, 16
	s_add_i32 s15, s15, 16
	s_add_i32 s17, s17, -16
	v_or_b32_e32 v20, s21, v14
	v_or_b32_e32 v22, s20, v5
	v_mad_i64_i32 v[20:21], s[20:21], v20, s12, v[12:13]
	v_mad_i64_i32 v[22:23], s[20:21], v22, s12, v[12:13]
	global_load_dword v82, v[20:21], off
	global_load_dword v83, v[22:23], off
	v_mad_u64_u32 v[100:101], s[20:21], v25, s60, v[4:5]
	v_mad_u64_u32 v[102:103], s[20:21], v24, s60, v[4:5]
	s_add_i32 s21, s19, 8
	s_add_i32 s20, s18, 8
	v_or_b32_e32 v24, s20, v1
	v_or_b32_e32 v25, s21, v0
	v_or_b32_e32 v20, s21, v14
	v_or_b32_e32 v22, s20, v5
	v_mad_i64_i32 v[20:21], s[20:21], v20, s12, v[12:13]
	v_mad_i64_i32 v[22:23], s[20:21], v22, s12, v[12:13]
	global_load_dword v84, v[20:21], off
	global_load_dword v85, v[22:23], off
	v_mad_u64_u32 v[104:105], s[20:21], v25, s60, v[4:5]
	v_mad_u64_u32 v[106:107], s[20:21], v24, s60, v[4:5]
	s_add_i32 s21, s19, 12
	s_add_i32 s20, s18, 12
	v_or_b32_e32 v24, s20, v1
	v_or_b32_e32 v25, s21, v0
	v_or_b32_e32 v20, s21, v14
	v_or_b32_e32 v22, s20, v5
	v_mad_i64_i32 v[20:21], s[20:21], v20, s12, v[12:13]
	v_mad_i64_i32 v[22:23], s[20:21], v22, s12, v[12:13]
	global_load_dword v86, v[20:21], off
	global_load_dword v87, v[22:23], off
	v_mad_u64_u32 v[108:109], s[20:21], v25, s60, v[4:5]
	v_mad_u64_u32 v[110:111], s[20:21], v24, s60, v[4:5]
	s_add_i32 s21, s19, 16
	s_add_i32 s20, s18, 16
	v_or_b32_e32 v24, s20, v1
	v_or_b32_e32 v25, s21, v0
	v_or_b32_e32 v20, s21, v14
	v_or_b32_e32 v22, s20, v5
	v_mad_i64_i32 v[20:21], s[20:21], v20, s12, v[12:13]
	v_mad_i64_i32 v[22:23], s[20:21], v22, s12, v[12:13]
	global_load_dword v88, v[20:21], off
	global_load_dword v89, v[22:23], off
	v_mad_u64_u32 v[112:113], s[20:21], v25, s60, v[4:5]
	v_mad_u64_u32 v[114:115], s[20:21], v24, s60, v[4:5]
	s_add_i32 s21, s19, 20
	s_add_i32 s20, s18, 20
	v_or_b32_e32 v24, s20, v1
	v_or_b32_e32 v25, s21, v0
	v_or_b32_e32 v20, s21, v14
	v_or_b32_e32 v22, s20, v5
	v_mad_i64_i32 v[20:21], s[20:21], v20, s12, v[12:13]
	v_mad_i64_i32 v[22:23], s[20:21], v22, s12, v[12:13]
	global_load_dword v90, v[20:21], off
	global_load_dword v91, v[22:23], off
	v_mad_u64_u32 v[116:117], s[20:21], v25, s60, v[4:5]
	v_mad_u64_u32 v[118:119], s[20:21], v24, s60, v[4:5]
	s_add_i32 s21, s19, 24
	s_add_i32 s20, s18, 24
	v_or_b32_e32 v24, s20, v1
	v_or_b32_e32 v25, s21, v0
	s_add_i32 s19, s19, 28
	s_add_i32 s18, s18, 28
	s_cmp_lg_u32 s17, 0
	v_or_b32_e32 v20, s21, v14
	v_or_b32_e32 v22, s20, v5
	v_mad_i64_i32 v[20:21], s[20:21], v20, s12, v[12:13]
	v_mad_i64_i32 v[22:23], s[20:21], v22, s12, v[12:13]
	global_load_dword v92, v[20:21], off
	global_load_dword v93, v[22:23], off
	v_mad_u64_u32 v[120:121], s[20:21], v25, s60, v[4:5]
	v_mad_u64_u32 v[122:123], s[20:21], v24, s60, v[4:5]
	v_or_b32_e32 v24, s18, v1
	v_or_b32_e32 v25, s19, v0
	v_or_b32_e32 v20, s19, v14
	v_or_b32_e32 v22, s18, v5
	v_mad_i64_i32 v[20:21], s[18:19], v20, s12, v[12:13]
	v_mad_i64_i32 v[22:23], s[18:19], v22, s12, v[12:13]
	global_load_dword v94, v[20:21], off
	global_load_dword v95, v[22:23], off
	v_mad_u64_u32 v[124:125], s[18:19], v25, s60, v[4:5]
	v_mad_u64_u32 v[126:127], s[18:19], v24, s60, v[4:5]
	s_waitcnt vmcnt(15)
	ds_write_b32 v96, v80
	s_waitcnt vmcnt(14)
	ds_write_b32 v98, v81
	s_waitcnt vmcnt(13)
	ds_write_b32 v100, v82
	s_waitcnt vmcnt(12)
	ds_write_b32 v102, v83
	s_waitcnt vmcnt(11)
	ds_write_b32 v104, v84
	s_waitcnt vmcnt(10)
	ds_write_b32 v106, v85
	s_waitcnt vmcnt(9)
	ds_write_b32 v108, v86
	s_waitcnt vmcnt(8)
	ds_write_b32 v110, v87
	s_waitcnt vmcnt(7)
	ds_write_b32 v112, v88
	s_waitcnt vmcnt(6)
	ds_write_b32 v114, v89
	s_waitcnt vmcnt(5)
	ds_write_b32 v116, v90
	s_waitcnt vmcnt(4)
	ds_write_b32 v118, v91
	s_waitcnt vmcnt(3)
	ds_write_b32 v120, v92
	s_waitcnt vmcnt(2)
	ds_write_b32 v122, v93
	s_waitcnt vmcnt(1)
	ds_write_b32 v124, v94
	s_waitcnt vmcnt(0)
	ds_write_b32 v126, v95
	s_cbranch_scc1 .LBB0_599
; #define LAS __attribute__((address_space(3)))
; __device__ __forceinline__ unsigned pk2(float lo, float hi) { unsigned r; asm("v_cvt_pk_bf16_f32 %0, %1, %2" : "=v"(r) : "v"(lo), "v"(hi)); return r; }
; __device__ __forceinline__ void transpose_item(const float* W, int K, int N, bf16_t* WT, LAS float* scr, int item, int lane, int perm_cols) {
;     ...
;     asm volatile("s_waitcnt lgkmcnt(0)" ::: "memory");
;     const int c = lane & 7;
; #pragma unroll
;     for (int j = 0; j < 4; ++j) { const int n = (lane >> 3) + 8 * j; const LAS float* s = scr + (8 * c) * 33 + n;
;         u32x4 o; o.x = pk2(s[0 * 33], s[1 * 33]); o.y = pk2(s[2 * 33], s[3 * 33]); o.z = pk2(s[4 * 33], s[5 * 33]); o.w = pk2(s[6 * 33], s[7 * 33]);
;         int rowi = n0 + n;
;         if (rowi < perm_cols) { const int oc = rowi & 255, part = oc >> 6, i6 = oc & 63; rowi = (rowi & ~255) + 128 * (part & 1) + 32 * (2 * (part >> 1) + (i6 >> 5)) + (i6 & 31); }
;         *(u32x4*)(WT + (size_t)rowi * K + k0 + 8 * c) = o; }
;     asm volatile("s_waitcnt lgkmcnt(0)" ::: "memory");
	s_lshl_b32 s15, s14, 6
	s_and_b32 s15, s15, 0x80
	s_lshr_b32 s16, s36, 1
	s_and_b32 s17, s36, 0xffffff20
	s_and_b32 s16, s16, 64
	s_or_b32 s15, s17, s15
	s_waitcnt lgkmcnt(0)
	s_or_b32 s15, s15, s16
	s_ashr_i32 s39, s38, 31
	ds_read2_b32 v[24:25], v15 offset0:33 offset1:41
	ds_read2_b32 v[26:27], v15 offset1:8
	s_cmp_lt_i32 s14, 0
	ds_read2_b32 v[28:29], v15 offset0:66 offset1:74
	ds_read2_b32 v[30:31], v15 offset0:99 offset1:107
	ds_read2_b32 v[32:33], v15 offset0:132 offset1:140
	ds_read2_b32 v[34:35], v15 offset0:165 offset1:173
	ds_read2_b32 v[36:37], v15 offset0:198 offset1:206
	ds_read2_b32 v[38:39], v15 offset0:231 offset1:239
	s_cselect_b32 s14, s15, s36
	v_or_b32_e32 v40, s14, v16
	v_ashrrev_i32_e32 v41, 31, v40
	v_lshl_add_u64 v[12:13], s[38:39], 1, v[10:11]
	v_lshlrev_b64 v[40:41], 12, v[40:41]
	s_waitcnt lgkmcnt(6)
	v_cvt_pk_bf16_f32 v20, v26, v24
	v_lshl_add_u64 v[40:41], v[12:13], 0, v[40:41]
	v_or_b32_e32 v24, s14, v17
	s_waitcnt lgkmcnt(4)
	v_cvt_pk_bf16_f32 v21, v28, v30
	s_waitcnt lgkmcnt(2)
	v_cvt_pk_bf16_f32 v22, v32, v34
	s_waitcnt lgkmcnt(0)
	v_cvt_pk_bf16_f32 v23, v36, v38
	global_store_dwordx4 v[40:41], v[20:23], off
	v_or_b32_e32 v40, s14, v18
	v_ashrrev_i32_e32 v41, 31, v40
	v_cvt_pk_bf16_f32 v20, v27, v25
	v_ashrrev_i32_e32 v25, 31, v24
	v_lshlrev_b64 v[24:25], 12, v[24:25]
	v_lshl_add_u64 v[24:25], v[12:13], 0, v[24:25]
	v_cvt_pk_bf16_f32 v21, v29, v31
	v_cvt_pk_bf16_f32 v22, v33, v35
	v_cvt_pk_bf16_f32 v23, v37, v39
	global_store_dwordx4 v[24:25], v[20:23], off
	ds_read2_b32 v[24:25], v15 offset0:16 offset1:24
	ds_read2_b32 v[26:27], v15 offset0:49 offset1:57
	ds_read2_b32 v[28:29], v15 offset0:82 offset1:90
	ds_read2_b32 v[30:31], v15 offset0:115 offset1:123
	ds_read2_b32 v[32:33], v15 offset0:148 offset1:156
	ds_read2_b32 v[34:35], v15 offset0:181 offset1:189
	ds_read2_b32 v[36:37], v15 offset0:214 offset1:222
	ds_read2_b32 v[38:39], v15 offset0:247 offset1:255
	v_lshlrev_b64 v[40:41], 12, v[40:41]
	s_waitcnt lgkmcnt(6)
	v_cvt_pk_bf16_f32 v20, v24, v26
	v_lshl_add_u64 v[40:41], v[12:13], 0, v[40:41]
	v_or_b32_e32 v24, s14, v19
	s_waitcnt lgkmcnt(4)
	v_cvt_pk_bf16_f32 v21, v28, v30
	s_waitcnt lgkmcnt(2)
	v_cvt_pk_bf16_f32 v22, v32, v34
	s_waitcnt lgkmcnt(0)
	v_cvt_pk_bf16_f32 v23, v36, v38
	global_store_dwordx4 v[40:41], v[20:23], off
	s_nop 1
	v_cvt_pk_bf16_f32 v20, v25, v27
	v_ashrrev_i32_e32 v25, 31, v24
	v_lshlrev_b64 v[24:25], 12, v[24:25]
	v_lshl_add_u64 v[12:13], v[12:13], 0, v[24:25]
	v_cvt_pk_bf16_f32 v21, v29, v31
	v_cvt_pk_bf16_f32 v22, v33, v35
	v_cvt_pk_bf16_f32 v23, v37, v39
	global_store_dwordx4 v[12:13], v[20:23], off
	s_waitcnt lgkmcnt(0)
	s_branch .LBB0_592
